# speedup vs baseline: 1.0006x; 1.0006x over previous
; __device__ __forceinline__ unsigned cvt_pk_bf16(float lo, float hi) { unsigned r; asm volatile("v_cvt_pk_bf16_f32 %0, %1, %2" : "=v"(r) : "v"(lo), "v"(hi)); return r; }
;     __device__ __forceinline__ void operator()(const f32x4 (&acc)[2][2][4][2], const Unit& u, int wr, int wc, int fr, int fq) const {
;         const int col0 = u.pn * BM + wc * 32 + 4 * fq;
; #pragma unroll
;         for (int ai = 0; ai < 2; ++ai)
; #pragma unroll
;             for (int m = 0; m < 4; ++m) { const int row = u.pm * BM + ai * HALF + wr * 64 + m * 16 + fr;
;                 const float* b = (row < HALF_TOK) ? base0 + (size_t)row * DM : base1 + (size_t)(row - HALF_TOK) * DM;
;                 float* o = out + (size_t)(row & omask) * DM; float sq = 0.f;
; #pragma unroll
;                 for (int bj = 0; bj < 2; ++bj)
; #pragma unroll
;                     for (int n = 0; n < 2; ++n) { const int c = col0 + bj * HALF + n * 16; const f32x4 bs = *(const f32x4*)(b + c); const f32x4 v = bs + acc[ai][bj][m][n]; *(f32x4*)(o + c) = v;
;                         if (xb) { sq += (v[0] * v[0] + v[1] * v[1]) + (v[2] * v[2] + v[3] * v[3]); *(u32x2*)(xb + (size_t)row * DM + c) = (u32x2){cvt_pk_bf16(v[0], v[1]), cvt_pk_bf16(v[2], v[3])}; } }
;                 if (xb) { sq += __shfl_xor(sq, 16); sq += __shfl_xor(sq, 32); if (fq == 0) ssq[(size_t)row * 32 + u.pn * 4 + wc] = sq; }
;                 if (m & 1) asm volatile("" ::: "memory"); }
;     }
.LBB0_78:
	s_lshl_b32 s4, s25, 8
	s_cmp_gt_u32 s4, s75
	s_cselect_b32 s44, s16, s14
	s_cselect_b32 s45, s17, s15
	s_cselect_b32 s5, 0x2000, 0
	s_sub_u32 s5, s4, s5
	s_lshl_b32 s5, s5, 13
	s_add_u32 s44, s44, s5
	s_addc_u32 s45, s45, 0
	s_and_b32 s5, s4, s34
	s_lshl_b32 s5, s5, 13
	s_add_u32 s46, s38, s5
	s_addc_u32 s47, s39, 0
	s_lshl_b32 s5, s4, 12
	s_add_u32 s48, s18, s5
	s_addc_u32 s49, s19, 0
	s_lshl_b32 s5, s4, 7
	s_add_u32 s66, s20, s5
	s_addc_u32 s67, s21, 0
	s_lshl_b32 s5, s0, 4
	s_add_u32 s66, s66, s5
	s_addc_u32 s67, s67, 0
	s_lshl_b32 s5, s35, 2
	s_add_u32 s66, s66, s5
	s_addc_u32 s67, s67, 0
	v_lshl_or_b32 v141, s0, 8, v154
	v_lshlrev_b32_e32 v142, 7, v152
	v_lshlrev_b32_e32 v140, 2, v141
	v_lshlrev_b32_e32 v141, 1, v141
	v_lshl_add_u32 v140, v152, 13, v140
	v_lshl_add_u32 v141, v152, 12, v141
	s_mov_b32 s4, s44
	s_mov_b32 s5, s45
	global_load_dwordx4 v[202:205], v140, s[4:5] offset:0
	global_load_dwordx4 v[206:209], v140, s[4:5] offset:64
	global_load_dwordx4 v[210:213], v140, s[4:5] offset:512
	global_load_dwordx4 v[214:217], v140, s[4:5] offset:576
	s_add_u32 s4, s44, 0x20000
	s_addc_u32 s5, s45, 0
	global_load_dwordx4 v[218:221], v140, s[4:5] offset:0
	global_load_dwordx4 v[222:225], v140, s[4:5] offset:64
	global_load_dwordx4 v[226:229], v140, s[4:5] offset:512
	global_load_dwordx4 v[230:233], v140, s[4:5] offset:576
	s_add_u32 s4, s44, 0x40000
	s_addc_u32 s5, s45, 0
	global_load_dwordx4 v[156:159], v140, s[4:5] offset:0
	global_load_dwordx4 v[160:163], v140, s[4:5] offset:64
	global_load_dwordx4 v[164:167], v140, s[4:5] offset:512
	global_load_dwordx4 v[168:171], v140, s[4:5] offset:576
	s_add_u32 s4, s44, 0x60000
	s_addc_u32 s5, s45, 0
	global_load_dwordx4 v[144:147], v140, s[4:5] offset:0
	global_load_dwordx4 v[148:151], v140, s[4:5] offset:64
	global_load_dwordx4 v[172:175], v140, s[4:5] offset:512
	global_load_dwordx4 v[176:179], v140, s[4:5] offset:576
	s_and_b64 vcc, exec, s[42:43]
	s_cbranch_vccz .Lepi_plain
	s_waitcnt vmcnt(12)
	v_pk_add_f32 v[124:125], v[124:125], v[202:203]
	v_pk_add_f32 v[126:127], v[126:127], v[204:205]
	v_pk_add_f32 v[120:121], v[120:121], v[206:207]
	v_pk_add_f32 v[122:123], v[122:123], v[208:209]
	v_pk_add_f32 v[116:117], v[116:117], v[210:211]
	v_pk_add_f32 v[118:119], v[118:119], v[212:213]
	v_pk_add_f32 v[112:113], v[112:113], v[214:215]
	v_pk_add_f32 v[114:115], v[114:115], v[216:217]
	s_mov_b32 s4, s46
	s_mov_b32 s5, s47
	global_store_dwordx4 v140, v[124:127], s[4:5] offset:0
	global_store_dwordx4 v140, v[120:123], s[4:5] offset:64
	global_store_dwordx4 v140, v[116:119], s[4:5] offset:512
	global_store_dwordx4 v140, v[112:115], s[4:5] offset:576
	v_cvt_pk_bf16_f32 v202, v124, v125
	v_cvt_pk_bf16_f32 v203, v126, v127
	v_mul_f32_e32 v236, v125, v125
	v_mul_f32_e32 v237, v127, v127
	v_fmac_f32_e32 v236, v124, v124
	v_fmac_f32_e32 v237, v126, v126
	v_add_f32_e32 v234, v236, v237
	v_cvt_pk_bf16_f32 v204, v120, v121
	v_cvt_pk_bf16_f32 v205, v122, v123
	v_mul_f32_e32 v236, v121, v121
	v_mul_f32_e32 v237, v123, v123
	v_fmac_f32_e32 v236, v120, v120
	v_fmac_f32_e32 v237, v122, v122
	v_add_f32_e32 v236, v236, v237
	v_add_f32_e32 v234, v234, v236
	v_cvt_pk_bf16_f32 v206, v116, v117
	v_cvt_pk_bf16_f32 v207, v118, v119
	v_mul_f32_e32 v236, v117, v117
	v_mul_f32_e32 v237, v119, v119
	v_fmac_f32_e32 v236, v116, v116
	v_fmac_f32_e32 v237, v118, v118
	v_add_f32_e32 v236, v236, v237
	v_add_f32_e32 v234, v234, v236
	v_cvt_pk_bf16_f32 v208, v112, v113
	v_cvt_pk_bf16_f32 v209, v114, v115
	v_mul_f32_e32 v236, v113, v113
	v_mul_f32_e32 v237, v115, v115
	v_fmac_f32_e32 v236, v112, v112
	v_fmac_f32_e32 v237, v114, v114
	v_add_f32_e32 v236, v236, v237
	v_add_f32_e32 v234, v234, v236
	s_mov_b32 s4, s48
	s_mov_b32 s5, s49
	global_store_dwordx2 v141, v[202:203], s[4:5] offset:0
	global_store_dwordx2 v141, v[204:205], s[4:5] offset:32
	global_store_dwordx2 v141, v[206:207], s[4:5] offset:256
	global_store_dwordx2 v141, v[208:209], s[4:5] offset:288
	v_mov_b32_e32 v235, v234
	s_nop 1
	v_permlane16_swap_b32_e32 v234, v235
	v_add_f32_e32 v234, v234, v235
	v_mov_b32_e32 v235, v234
	s_nop 1
	v_permlane32_swap_b32_e32 v234, v235
	v_add_f32_e32 v234, v234, v235
	s_mov_b32 s4, s66
	s_mov_b32 s5, s67
	s_and_saveexec_b64 s[10:11], s[6:7]
	global_store_dword v142, v234, s[4:5]
	s_mov_b64 exec, s[10:11]
	s_add_u32 s4, s44, 0x100000
	s_addc_u32 s5, s45, 0
	global_load_dwordx4 v[202:205], v140, s[4:5] offset:0
	global_load_dwordx4 v[206:209], v140, s[4:5] offset:64
	global_load_dwordx4 v[210:213], v140, s[4:5] offset:512
	global_load_dwordx4 v[214:217], v140, s[4:5] offset:576
	s_waitcnt vmcnt(21)
; __device__ __forceinline__ unsigned cvt_pk_bf16(float lo, float hi) { unsigned r; asm volatile("v_cvt_pk_bf16_f32 %0, %1, %2" : "=v"(r) : "v"(lo), "v"(hi)); return r; }
;     __device__ __forceinline__ void operator()(const f32x4 (&acc)[2][2][4][2], const Unit& u, int wr, int wc, int fr, int fq) const {
;         const int col0 = u.pn * BM + wc * 32 + 4 * fq;
; #pragma unroll
;         for (int ai = 0; ai < 2; ++ai)
; #pragma unroll
;             for (int m = 0; m < 4; ++m) { const int row = u.pm * BM + ai * HALF + wr * 64 + m * 16 + fr;
;                 const float* b = (row < HALF_TOK) ? base0 + (size_t)row * DM : base1 + (size_t)(row - HALF_TOK) * DM;
;                 float* o = out + (size_t)(row & omask) * DM; float sq = 0.f;
; #pragma unroll
;                 for (int bj = 0; bj < 2; ++bj)
; #pragma unroll
;                     for (int n = 0; n < 2; ++n) { const int c = col0 + bj * HALF + n * 16; const f32x4 bs = *(const f32x4*)(b + c); const f32x4 v = bs + acc[ai][bj][m][n]; *(f32x4*)(o + c) = v;
;                         if (xb) { sq += (v[0] * v[0] + v[1] * v[1]) + (v[2] * v[2] + v[3] * v[3]); *(u32x2*)(xb + (size_t)row * DM + c) = (u32x2){cvt_pk_bf16(v[0], v[1]), cvt_pk_bf16(v[2], v[3])}; } }
;                 if (xb) { sq += __shfl_xor(sq, 16); sq += __shfl_xor(sq, 32); if (fq == 0) ssq[(size_t)row * 32 + u.pn * 4 + wc] = sq; }
;                 if (m & 1) asm volatile("" ::: "memory"); }
;     }
	v_pk_add_f32 v[108:109], v[108:109], v[218:219]
	v_pk_add_f32 v[110:111], v[110:111], v[220:221]
	v_pk_add_f32 v[104:105], v[104:105], v[222:223]
	v_pk_add_f32 v[106:107], v[106:107], v[224:225]
	v_pk_add_f32 v[100:101], v[100:101], v[226:227]
	v_pk_add_f32 v[102:103], v[102:103], v[228:229]
	v_pk_add_f32 v[96:97], v[96:97], v[230:231]
	v_pk_add_f32 v[98:99], v[98:99], v[232:233]
	s_add_u32 s4, s46, 0x20000
	s_addc_u32 s5, s47, 0
	global_store_dwordx4 v140, v[108:111], s[4:5] offset:0
	global_store_dwordx4 v140, v[104:107], s[4:5] offset:64
	global_store_dwordx4 v140, v[100:103], s[4:5] offset:512
	global_store_dwordx4 v140, v[96:99], s[4:5] offset:576
	v_cvt_pk_bf16_f32 v218, v108, v109
	v_cvt_pk_bf16_f32 v219, v110, v111
	v_mul_f32_e32 v236, v109, v109
	v_mul_f32_e32 v237, v111, v111
	v_fmac_f32_e32 v236, v108, v108
	v_fmac_f32_e32 v237, v110, v110
	v_add_f32_e32 v234, v236, v237
	v_cvt_pk_bf16_f32 v220, v104, v105
	v_cvt_pk_bf16_f32 v221, v106, v107
	v_mul_f32_e32 v236, v105, v105
	v_mul_f32_e32 v237, v107, v107
	v_fmac_f32_e32 v236, v104, v104
	v_fmac_f32_e32 v237, v106, v106
	v_add_f32_e32 v236, v236, v237
	v_add_f32_e32 v234, v234, v236
	v_cvt_pk_bf16_f32 v222, v100, v101
	v_cvt_pk_bf16_f32 v223, v102, v103
	v_mul_f32_e32 v236, v101, v101
	v_mul_f32_e32 v237, v103, v103
	v_fmac_f32_e32 v236, v100, v100
	v_fmac_f32_e32 v237, v102, v102
	v_add_f32_e32 v236, v236, v237
	v_add_f32_e32 v234, v234, v236
	v_cvt_pk_bf16_f32 v224, v96, v97
	v_cvt_pk_bf16_f32 v225, v98, v99
	v_mul_f32_e32 v236, v97, v97
	v_mul_f32_e32 v237, v99, v99
	v_fmac_f32_e32 v236, v96, v96
	v_fmac_f32_e32 v237, v98, v98
	v_add_f32_e32 v236, v236, v237
	v_add_f32_e32 v234, v234, v236
	s_add_u32 s4, s48, 0x10000
	s_addc_u32 s5, s49, 0
	global_store_dwordx2 v141, v[218:219], s[4:5] offset:0
	global_store_dwordx2 v141, v[220:221], s[4:5] offset:32
	global_store_dwordx2 v141, v[222:223], s[4:5] offset:256
	global_store_dwordx2 v141, v[224:225], s[4:5] offset:288
	v_mov_b32_e32 v235, v234
	s_nop 1
	v_permlane16_swap_b32_e32 v234, v235
	v_add_f32_e32 v234, v234, v235
	v_mov_b32_e32 v235, v234
	s_nop 1
	v_permlane32_swap_b32_e32 v234, v235
	v_add_f32_e32 v234, v234, v235
	s_add_u32 s4, s66, 0x800
	s_addc_u32 s5, s67, 0
	s_and_saveexec_b64 s[10:11], s[6:7]
	global_store_dword v142, v234, s[4:5]
	s_mov_b64 exec, s[10:11]
	s_add_u32 s4, s44, 0x120000
	s_addc_u32 s5, s45, 0
	global_load_dwordx4 v[218:221], v140, s[4:5] offset:0
	global_load_dwordx4 v[222:225], v140, s[4:5] offset:64
	global_load_dwordx4 v[226:229], v140, s[4:5] offset:512
	global_load_dwordx4 v[230:233], v140, s[4:5] offset:576
	s_waitcnt vmcnt(30)
	v_pk_add_f32 v[92:93], v[92:93], v[156:157]
	v_pk_add_f32 v[94:95], v[94:95], v[158:159]
	v_pk_add_f32 v[88:89], v[88:89], v[160:161]
	v_pk_add_f32 v[90:91], v[90:91], v[162:163]
	v_pk_add_f32 v[84:85], v[84:85], v[164:165]
	v_pk_add_f32 v[86:87], v[86:87], v[166:167]
	v_pk_add_f32 v[80:81], v[80:81], v[168:169]
	v_pk_add_f32 v[82:83], v[82:83], v[170:171]
	s_add_u32 s4, s46, 0x40000
	s_addc_u32 s5, s47, 0
	global_store_dwordx4 v140, v[92:95], s[4:5] offset:0
	global_store_dwordx4 v140, v[88:91], s[4:5] offset:64
	global_store_dwordx4 v140, v[84:87], s[4:5] offset:512
	global_store_dwordx4 v140, v[80:83], s[4:5] offset:576
	v_cvt_pk_bf16_f32 v156, v92, v93
	v_cvt_pk_bf16_f32 v157, v94, v95
	v_mul_f32_e32 v236, v93, v93
	v_mul_f32_e32 v237, v95, v95
	v_fmac_f32_e32 v236, v92, v92
	v_fmac_f32_e32 v237, v94, v94
	v_add_f32_e32 v234, v236, v237
	v_cvt_pk_bf16_f32 v158, v88, v89
	v_cvt_pk_bf16_f32 v159, v90, v91
	v_mul_f32_e32 v236, v89, v89
	v_mul_f32_e32 v237, v91, v91
	v_fmac_f32_e32 v236, v88, v88
	v_fmac_f32_e32 v237, v90, v90
	v_add_f32_e32 v236, v236, v237
	v_add_f32_e32 v234, v234, v236
	v_cvt_pk_bf16_f32 v160, v84, v85
	v_cvt_pk_bf16_f32 v161, v86, v87
	v_mul_f32_e32 v236, v85, v85
	v_mul_f32_e32 v237, v87, v87
	v_fmac_f32_e32 v236, v84, v84
	v_fmac_f32_e32 v237, v86, v86
	v_add_f32_e32 v236, v236, v237
	v_add_f32_e32 v234, v234, v236
	v_cvt_pk_bf16_f32 v162, v80, v81
	v_cvt_pk_bf16_f32 v163, v82, v83
	v_mul_f32_e32 v236, v81, v81
	v_mul_f32_e32 v237, v83, v83
	v_fmac_f32_e32 v236, v80, v80
	v_fmac_f32_e32 v237, v82, v82
	v_add_f32_e32 v236, v236, v237
	v_add_f32_e32 v234, v234, v236
	s_add_u32 s4, s48, 0x20000
	s_addc_u32 s5, s49, 0
	global_store_dwordx2 v141, v[156:157], s[4:5] offset:0
	global_store_dwordx2 v141, v[158:159], s[4:5] offset:32
	global_store_dwordx2 v141, v[160:161], s[4:5] offset:256
	global_store_dwordx2 v141, v[162:163], s[4:5] offset:288
	v_mov_b32_e32 v235, v234
	s_nop 1
	v_permlane16_swap_b32_e32 v234, v235
	v_add_f32_e32 v234, v234, v235
	v_mov_b32_e32 v235, v234
	s_nop 1
	v_permlane32_swap_b32_e32 v234, v235
	v_add_f32_e32 v234, v234, v235
	s_add_u32 s4, s66, 0x1000
	s_addc_u32 s5, s67, 0
	s_and_saveexec_b64 s[10:11], s[6:7]
	global_store_dword v142, v234, s[4:5]
	s_mov_b64 exec, s[10:11]
	s_add_u32 s4, s44, 0x140000
	s_addc_u32 s5, s45, 0
	global_load_dwordx4 v[156:159], v140, s[4:5] offset:0
	global_load_dwordx4 v[160:163], v140, s[4:5] offset:64
	global_load_dwordx4 v[164:167], v140, s[4:5] offset:512
	global_load_dwordx4 v[168:171], v140, s[4:5] offset:576
	s_waitcnt vmcnt(39)
; __device__ __forceinline__ unsigned cvt_pk_bf16(float lo, float hi) { unsigned r; asm volatile("v_cvt_pk_bf16_f32 %0, %1, %2" : "=v"(r) : "v"(lo), "v"(hi)); return r; }
;     __device__ __forceinline__ void operator()(const f32x4 (&acc)[2][2][4][2], const Unit& u, int wr, int wc, int fr, int fq) const {
;         const int col0 = u.pn * BM + wc * 32 + 4 * fq;
; #pragma unroll
;         for (int ai = 0; ai < 2; ++ai)
; #pragma unroll
;             for (int m = 0; m < 4; ++m) { const int row = u.pm * BM + ai * HALF + wr * 64 + m * 16 + fr;
;                 const float* b = (row < HALF_TOK) ? base0 + (size_t)row * DM : base1 + (size_t)(row - HALF_TOK) * DM;
;                 float* o = out + (size_t)(row & omask) * DM; float sq = 0.f;
; #pragma unroll
;                 for (int bj = 0; bj < 2; ++bj)
; #pragma unroll
;                     for (int n = 0; n < 2; ++n) { const int c = col0 + bj * HALF + n * 16; const f32x4 bs = *(const f32x4*)(b + c); const f32x4 v = bs + acc[ai][bj][m][n]; *(f32x4*)(o + c) = v;
;                         if (xb) { sq += (v[0] * v[0] + v[1] * v[1]) + (v[2] * v[2] + v[3] * v[3]); *(u32x2*)(xb + (size_t)row * DM + c) = (u32x2){cvt_pk_bf16(v[0], v[1]), cvt_pk_bf16(v[2], v[3])}; } }
;                 if (xb) { sq += __shfl_xor(sq, 16); sq += __shfl_xor(sq, 32); if (fq == 0) ssq[(size_t)row * 32 + u.pn * 4 + wc] = sq; }
;                 if (m & 1) asm volatile("" ::: "memory"); }
;     }
	v_pk_add_f32 v[76:77], v[76:77], v[144:145]
	v_pk_add_f32 v[78:79], v[78:79], v[146:147]
	v_pk_add_f32 v[72:73], v[72:73], v[148:149]
	v_pk_add_f32 v[74:75], v[74:75], v[150:151]
	v_pk_add_f32 v[68:69], v[68:69], v[172:173]
	v_pk_add_f32 v[70:71], v[70:71], v[174:175]
	v_pk_add_f32 v[64:65], v[64:65], v[176:177]
	v_pk_add_f32 v[66:67], v[66:67], v[178:179]
	s_add_u32 s4, s46, 0x60000
	s_addc_u32 s5, s47, 0
	global_store_dwordx4 v140, v[76:79], s[4:5] offset:0
	global_store_dwordx4 v140, v[72:75], s[4:5] offset:64
	global_store_dwordx4 v140, v[68:71], s[4:5] offset:512
	global_store_dwordx4 v140, v[64:67], s[4:5] offset:576
	v_cvt_pk_bf16_f32 v144, v76, v77
	v_cvt_pk_bf16_f32 v145, v78, v79
	v_mul_f32_e32 v236, v77, v77
	v_mul_f32_e32 v237, v79, v79
	v_fmac_f32_e32 v236, v76, v76
	v_fmac_f32_e32 v237, v78, v78
	v_add_f32_e32 v234, v236, v237
	v_cvt_pk_bf16_f32 v146, v72, v73
	v_cvt_pk_bf16_f32 v147, v74, v75
	v_mul_f32_e32 v236, v73, v73
	v_mul_f32_e32 v237, v75, v75
	v_fmac_f32_e32 v236, v72, v72
	v_fmac_f32_e32 v237, v74, v74
	v_add_f32_e32 v236, v236, v237
	v_add_f32_e32 v234, v234, v236
	v_cvt_pk_bf16_f32 v148, v68, v69
	v_cvt_pk_bf16_f32 v149, v70, v71
	v_mul_f32_e32 v236, v69, v69
	v_mul_f32_e32 v237, v71, v71
	v_fmac_f32_e32 v236, v68, v68
	v_fmac_f32_e32 v237, v70, v70
	v_add_f32_e32 v236, v236, v237
	v_add_f32_e32 v234, v234, v236
	v_cvt_pk_bf16_f32 v150, v64, v65
	v_cvt_pk_bf16_f32 v151, v66, v67
	v_mul_f32_e32 v236, v65, v65
	v_mul_f32_e32 v237, v67, v67
	v_fmac_f32_e32 v236, v64, v64
	v_fmac_f32_e32 v237, v66, v66
	v_add_f32_e32 v236, v236, v237
	v_add_f32_e32 v234, v234, v236
	s_add_u32 s4, s48, 0x30000
	s_addc_u32 s5, s49, 0
	global_store_dwordx2 v141, v[144:145], s[4:5] offset:0
	global_store_dwordx2 v141, v[146:147], s[4:5] offset:32
	global_store_dwordx2 v141, v[148:149], s[4:5] offset:256
	global_store_dwordx2 v141, v[150:151], s[4:5] offset:288
	v_mov_b32_e32 v235, v234
	s_nop 1
	v_permlane16_swap_b32_e32 v234, v235
	v_add_f32_e32 v234, v234, v235
	v_mov_b32_e32 v235, v234
	s_nop 1
	v_permlane32_swap_b32_e32 v234, v235
	v_add_f32_e32 v234, v234, v235
	s_add_u32 s4, s66, 0x1800
	s_addc_u32 s5, s67, 0
	s_and_saveexec_b64 s[10:11], s[6:7]
	global_store_dword v142, v234, s[4:5]
	s_mov_b64 exec, s[10:11]
	s_add_u32 s4, s44, 0x160000
	s_addc_u32 s5, s45, 0
	global_load_dwordx4 v[144:147], v140, s[4:5] offset:0
	global_load_dwordx4 v[148:151], v140, s[4:5] offset:64
	global_load_dwordx4 v[172:175], v140, s[4:5] offset:512
	global_load_dwordx4 v[176:179], v140, s[4:5] offset:576
	s_waitcnt vmcnt(39)
	v_pk_add_f32 v[60:61], v[60:61], v[202:203]
	v_pk_add_f32 v[62:63], v[62:63], v[204:205]
	v_pk_add_f32 v[56:57], v[56:57], v[206:207]
	v_pk_add_f32 v[58:59], v[58:59], v[208:209]
	v_pk_add_f32 v[52:53], v[52:53], v[210:211]
	v_pk_add_f32 v[54:55], v[54:55], v[212:213]
	v_pk_add_f32 v[48:49], v[48:49], v[214:215]
	v_pk_add_f32 v[50:51], v[50:51], v[216:217]
	s_add_u32 s4, s46, 0x100000
	s_addc_u32 s5, s47, 0
	global_store_dwordx4 v140, v[60:63], s[4:5] offset:0
	global_store_dwordx4 v140, v[56:59], s[4:5] offset:64
	global_store_dwordx4 v140, v[52:55], s[4:5] offset:512
	global_store_dwordx4 v140, v[48:51], s[4:5] offset:576
	v_cvt_pk_bf16_f32 v202, v60, v61
	v_cvt_pk_bf16_f32 v203, v62, v63
	v_mul_f32_e32 v236, v61, v61
	v_mul_f32_e32 v237, v63, v63
	v_fmac_f32_e32 v236, v60, v60
	v_fmac_f32_e32 v237, v62, v62
	v_add_f32_e32 v234, v236, v237
	v_cvt_pk_bf16_f32 v204, v56, v57
	v_cvt_pk_bf16_f32 v205, v58, v59
	v_mul_f32_e32 v236, v57, v57
	v_mul_f32_e32 v237, v59, v59
	v_fmac_f32_e32 v236, v56, v56
	v_fmac_f32_e32 v237, v58, v58
	v_add_f32_e32 v236, v236, v237
	v_add_f32_e32 v234, v234, v236
	v_cvt_pk_bf16_f32 v206, v52, v53
	v_cvt_pk_bf16_f32 v207, v54, v55
	v_mul_f32_e32 v236, v53, v53
	v_mul_f32_e32 v237, v55, v55
	v_fmac_f32_e32 v236, v52, v52
	v_fmac_f32_e32 v237, v54, v54
	v_add_f32_e32 v236, v236, v237
	v_add_f32_e32 v234, v234, v236
	v_cvt_pk_bf16_f32 v208, v48, v49
	v_cvt_pk_bf16_f32 v209, v50, v51
	v_mul_f32_e32 v236, v49, v49
	v_mul_f32_e32 v237, v51, v51
	v_fmac_f32_e32 v236, v48, v48
	v_fmac_f32_e32 v237, v50, v50
	v_add_f32_e32 v236, v236, v237
	v_add_f32_e32 v234, v234, v236
	s_add_u32 s4, s48, 0x80000
	s_addc_u32 s5, s49, 0
	global_store_dwordx2 v141, v[202:203], s[4:5] offset:0
	global_store_dwordx2 v141, v[204:205], s[4:5] offset:32
	global_store_dwordx2 v141, v[206:207], s[4:5] offset:256
	global_store_dwordx2 v141, v[208:209], s[4:5] offset:288
	v_mov_b32_e32 v235, v234
	s_nop 1
	v_permlane16_swap_b32_e32 v234, v235
	v_add_f32_e32 v234, v234, v235
	v_mov_b32_e32 v235, v234
	s_nop 1
	v_permlane32_swap_b32_e32 v234, v235
	v_add_f32_e32 v234, v234, v235
	s_add_u32 s4, s66, 0x4000
	s_addc_u32 s5, s67, 0
	s_and_saveexec_b64 s[10:11], s[6:7]
	global_store_dword v142, v234, s[4:5]
	s_mov_b64 exec, s[10:11]
	s_waitcnt vmcnt(35)
; __device__ __forceinline__ unsigned cvt_pk_bf16(float lo, float hi) { unsigned r; asm volatile("v_cvt_pk_bf16_f32 %0, %1, %2" : "=v"(r) : "v"(lo), "v"(hi)); return r; }
;     __device__ __forceinline__ void operator()(const f32x4 (&acc)[2][2][4][2], const Unit& u, int wr, int wc, int fr, int fq) const {
;         const int col0 = u.pn * BM + wc * 32 + 4 * fq;
; #pragma unroll
;         for (int ai = 0; ai < 2; ++ai)
; #pragma unroll
;             for (int m = 0; m < 4; ++m) { const int row = u.pm * BM + ai * HALF + wr * 64 + m * 16 + fr;
;                 const float* b = (row < HALF_TOK) ? base0 + (size_t)row * DM : base1 + (size_t)(row - HALF_TOK) * DM;
;                 float* o = out + (size_t)(row & omask) * DM; float sq = 0.f;
; #pragma unroll
;                 for (int bj = 0; bj < 2; ++bj)
; #pragma unroll
;                     for (int n = 0; n < 2; ++n) { const int c = col0 + bj * HALF + n * 16; const f32x4 bs = *(const f32x4*)(b + c); const f32x4 v = bs + acc[ai][bj][m][n]; *(f32x4*)(o + c) = v;
;                         if (xb) { sq += (v[0] * v[0] + v[1] * v[1]) + (v[2] * v[2] + v[3] * v[3]); *(u32x2*)(xb + (size_t)row * DM + c) = (u32x2){cvt_pk_bf16(v[0], v[1]), cvt_pk_bf16(v[2], v[3])}; } }
;                 if (xb) { sq += __shfl_xor(sq, 16); sq += __shfl_xor(sq, 32); if (fq == 0) ssq[(size_t)row * 32 + u.pn * 4 + wc] = sq; }
;                 if (m & 1) asm volatile("" ::: "memory"); }
;     }
	v_pk_add_f32 v[44:45], v[44:45], v[218:219]
	v_pk_add_f32 v[46:47], v[46:47], v[220:221]
	v_pk_add_f32 v[40:41], v[40:41], v[222:223]
	v_pk_add_f32 v[42:43], v[42:43], v[224:225]
	v_pk_add_f32 v[36:37], v[36:37], v[226:227]
	v_pk_add_f32 v[38:39], v[38:39], v[228:229]
	v_pk_add_f32 v[32:33], v[32:33], v[230:231]
	v_pk_add_f32 v[34:35], v[34:35], v[232:233]
	s_add_u32 s4, s46, 0x120000
	s_addc_u32 s5, s47, 0
	global_store_dwordx4 v140, v[44:47], s[4:5] offset:0
	global_store_dwordx4 v140, v[40:43], s[4:5] offset:64
	global_store_dwordx4 v140, v[36:39], s[4:5] offset:512
	global_store_dwordx4 v140, v[32:35], s[4:5] offset:576
	v_cvt_pk_bf16_f32 v218, v44, v45
	v_cvt_pk_bf16_f32 v219, v46, v47
	v_mul_f32_e32 v236, v45, v45
	v_mul_f32_e32 v237, v47, v47
	v_fmac_f32_e32 v236, v44, v44
	v_fmac_f32_e32 v237, v46, v46
	v_add_f32_e32 v234, v236, v237
	v_cvt_pk_bf16_f32 v220, v40, v41
	v_cvt_pk_bf16_f32 v221, v42, v43
	v_mul_f32_e32 v236, v41, v41
	v_mul_f32_e32 v237, v43, v43
	v_fmac_f32_e32 v236, v40, v40
	v_fmac_f32_e32 v237, v42, v42
	v_add_f32_e32 v236, v236, v237
	v_add_f32_e32 v234, v234, v236
	v_cvt_pk_bf16_f32 v222, v36, v37
	v_cvt_pk_bf16_f32 v223, v38, v39
	v_mul_f32_e32 v236, v37, v37
	v_mul_f32_e32 v237, v39, v39
	v_fmac_f32_e32 v236, v36, v36
	v_fmac_f32_e32 v237, v38, v38
	v_add_f32_e32 v236, v236, v237
	v_add_f32_e32 v234, v234, v236
	v_cvt_pk_bf16_f32 v224, v32, v33
	v_cvt_pk_bf16_f32 v225, v34, v35
	v_mul_f32_e32 v236, v33, v33
	v_mul_f32_e32 v237, v35, v35
	v_fmac_f32_e32 v236, v32, v32
	v_fmac_f32_e32 v237, v34, v34
	v_add_f32_e32 v236, v236, v237
	v_add_f32_e32 v234, v234, v236
	s_add_u32 s4, s48, 0x90000
	s_addc_u32 s5, s49, 0
	global_store_dwordx2 v141, v[218:219], s[4:5] offset:0
	global_store_dwordx2 v141, v[220:221], s[4:5] offset:32
	global_store_dwordx2 v141, v[222:223], s[4:5] offset:256
	global_store_dwordx2 v141, v[224:225], s[4:5] offset:288
	v_mov_b32_e32 v235, v234
	s_nop 1
	v_permlane16_swap_b32_e32 v234, v235
	v_add_f32_e32 v234, v234, v235
	v_mov_b32_e32 v235, v234
	s_nop 1
	v_permlane32_swap_b32_e32 v234, v235
	v_add_f32_e32 v234, v234, v235
	s_add_u32 s4, s66, 0x4800
	s_addc_u32 s5, s67, 0
	s_and_saveexec_b64 s[10:11], s[6:7]
	global_store_dword v142, v234, s[4:5]
	s_mov_b64 exec, s[10:11]
	s_waitcnt vmcnt(31)
	v_pk_add_f32 v[28:29], v[28:29], v[156:157]
	v_pk_add_f32 v[30:31], v[30:31], v[158:159]
	v_pk_add_f32 v[24:25], v[24:25], v[160:161]
	v_pk_add_f32 v[26:27], v[26:27], v[162:163]
	v_pk_add_f32 v[20:21], v[20:21], v[164:165]
	v_pk_add_f32 v[22:23], v[22:23], v[166:167]
	v_pk_add_f32 v[16:17], v[16:17], v[168:169]
	v_pk_add_f32 v[18:19], v[18:19], v[170:171]
	s_add_u32 s4, s46, 0x140000
	s_addc_u32 s5, s47, 0
	global_store_dwordx4 v140, v[28:31], s[4:5] offset:0
	global_store_dwordx4 v140, v[24:27], s[4:5] offset:64
	global_store_dwordx4 v140, v[20:23], s[4:5] offset:512
	global_store_dwordx4 v140, v[16:19], s[4:5] offset:576
	v_cvt_pk_bf16_f32 v156, v28, v29
	v_cvt_pk_bf16_f32 v157, v30, v31
	v_mul_f32_e32 v236, v29, v29
	v_mul_f32_e32 v237, v31, v31
	v_fmac_f32_e32 v236, v28, v28
	v_fmac_f32_e32 v237, v30, v30
	v_add_f32_e32 v234, v236, v237
	v_cvt_pk_bf16_f32 v158, v24, v25
	v_cvt_pk_bf16_f32 v159, v26, v27
	v_mul_f32_e32 v236, v25, v25
	v_mul_f32_e32 v237, v27, v27
	v_fmac_f32_e32 v236, v24, v24
	v_fmac_f32_e32 v237, v26, v26
	v_add_f32_e32 v236, v236, v237
	v_add_f32_e32 v234, v234, v236
	v_cvt_pk_bf16_f32 v160, v20, v21
	v_cvt_pk_bf16_f32 v161, v22, v23
	v_mul_f32_e32 v236, v21, v21
	v_mul_f32_e32 v237, v23, v23
	v_fmac_f32_e32 v236, v20, v20
	v_fmac_f32_e32 v237, v22, v22
	v_add_f32_e32 v236, v236, v237
	v_add_f32_e32 v234, v234, v236
	v_cvt_pk_bf16_f32 v162, v16, v17
	v_cvt_pk_bf16_f32 v163, v18, v19
	v_mul_f32_e32 v236, v17, v17
	v_mul_f32_e32 v237, v19, v19
	v_fmac_f32_e32 v236, v16, v16
	v_fmac_f32_e32 v237, v18, v18
	v_add_f32_e32 v236, v236, v237
	v_add_f32_e32 v234, v234, v236
	s_add_u32 s4, s48, 0xa0000
	s_addc_u32 s5, s49, 0
	global_store_dwordx2 v141, v[156:157], s[4:5] offset:0
	global_store_dwordx2 v141, v[158:159], s[4:5] offset:32
	global_store_dwordx2 v141, v[160:161], s[4:5] offset:256
	global_store_dwordx2 v141, v[162:163], s[4:5] offset:288
	v_mov_b32_e32 v235, v234
	s_nop 1
	v_permlane16_swap_b32_e32 v234, v235
	v_add_f32_e32 v234, v234, v235
	v_mov_b32_e32 v235, v234
	s_nop 1
	v_permlane32_swap_b32_e32 v234, v235
	v_add_f32_e32 v234, v234, v235
	s_add_u32 s4, s66, 0x5000
	s_addc_u32 s5, s67, 0
	s_and_saveexec_b64 s[10:11], s[6:7]
	global_store_dword v142, v234, s[4:5]
	s_mov_b64 exec, s[10:11]
	s_waitcnt vmcnt(27)
	v_pk_add_f32 v[12:13], v[12:13], v[144:145]
	v_pk_add_f32 v[14:15], v[14:15], v[146:147]
	v_pk_add_f32 v[8:9], v[8:9], v[148:149]
	v_pk_add_f32 v[10:11], v[10:11], v[150:151]
	v_pk_add_f32 v[4:5], v[4:5], v[172:173]
	v_pk_add_f32 v[6:7], v[6:7], v[174:175]
	v_pk_add_f32 v[0:1], v[0:1], v[176:177]
	v_pk_add_f32 v[2:3], v[2:3], v[178:179]
	s_add_u32 s4, s46, 0x160000
	s_addc_u32 s5, s47, 0
	global_store_dwordx4 v140, v[12:15], s[4:5] offset:0
	global_store_dwordx4 v140, v[8:11], s[4:5] offset:64
	global_store_dwordx4 v140, v[4:7], s[4:5] offset:512
	global_store_dwordx4 v140, v[0:3], s[4:5] offset:576
	v_cvt_pk_bf16_f32 v144, v12, v13
	v_cvt_pk_bf16_f32 v145, v14, v15
	v_mul_f32_e32 v236, v13, v13
	v_mul_f32_e32 v237, v15, v15
	v_fmac_f32_e32 v236, v12, v12
	v_fmac_f32_e32 v237, v14, v14
	v_add_f32_e32 v234, v236, v237
	v_cvt_pk_bf16_f32 v146, v8, v9
	v_cvt_pk_bf16_f32 v147, v10, v11
	v_mul_f32_e32 v236, v9, v9
	v_mul_f32_e32 v237, v11, v11
	v_fmac_f32_e32 v236, v8, v8
	v_fmac_f32_e32 v237, v10, v10
	v_add_f32_e32 v236, v236, v237
	v_add_f32_e32 v234, v234, v236
	v_cvt_pk_bf16_f32 v148, v4, v5
	v_cvt_pk_bf16_f32 v149, v6, v7
	v_mul_f32_e32 v236, v5, v5
	v_mul_f32_e32 v237, v7, v7
	v_fmac_f32_e32 v236, v4, v4
	v_fmac_f32_e32 v237, v6, v6
	v_add_f32_e32 v236, v236, v237
	v_add_f32_e32 v234, v234, v236
	v_cvt_pk_bf16_f32 v150, v0, v1
	v_cvt_pk_bf16_f32 v151, v2, v3
	v_mul_f32_e32 v236, v1, v1
	v_mul_f32_e32 v237, v3, v3
	v_fmac_f32_e32 v236, v0, v0
	v_fmac_f32_e32 v237, v2, v2
	v_add_f32_e32 v236, v236, v237
	v_add_f32_e32 v234, v234, v236
	s_add_u32 s4, s48, 0xb0000
	s_addc_u32 s5, s49, 0
	global_store_dwordx2 v141, v[144:145], s[4:5] offset:0
	global_store_dwordx2 v141, v[146:147], s[4:5] offset:32
	global_store_dwordx2 v141, v[148:149], s[4:5] offset:256
	global_store_dwordx2 v141, v[150:151], s[4:5] offset:288
	v_mov_b32_e32 v235, v234
	s_nop 1
	v_permlane16_swap_b32_e32 v234, v235
	v_add_f32_e32 v234, v234, v235
	v_mov_b32_e32 v235, v234
	s_nop 1
	v_permlane32_swap_b32_e32 v234, v235
	v_add_f32_e32 v234, v234, v235
	s_add_u32 s4, s66, 0x5800
	s_addc_u32 s5, s67, 0
	s_and_saveexec_b64 s[10:11], s[6:7]
	global_store_dword v142, v234, s[4:5]
	s_mov_b64 exec, s[10:11]
	s_branch .Lepi_done
; __device__ __forceinline__ unsigned cvt_pk_bf16(float lo, float hi) { unsigned r; asm volatile("v_cvt_pk_bf16_f32 %0, %1, %2" : "=v"(r) : "v"(lo), "v"(hi)); return r; }
; __device__ __forceinline__ float opaque_zero() { float z; asm volatile("v_mov_b32 %0, 0" : "=v"(z)); return z; }
; #define PG8_BAR __builtin_amdgcn_s_barrier()
;     __device__ __forceinline__ void operator()(const f32x4 (&acc)[2][2][4][2], const Unit& u, int wr, int wc, int fr, int fq) const {
;         const int col0 = u.pn * BM + wc * 32 + 4 * fq;
; #pragma unroll
;         for (int ai = 0; ai < 2; ++ai)
; #pragma unroll
;             for (int m = 0; m < 4; ++m) { const int row = u.pm * BM + ai * HALF + wr * 64 + m * 16 + fr;
;                 const float* b = (row < HALF_TOK) ? base0 + (size_t)row * DM : base1 + (size_t)(row - HALF_TOK) * DM;
;                 float* o = out + (size_t)(row & omask) * DM; float sq = 0.f;
; #pragma unroll
;                 for (int bj = 0; bj < 2; ++bj)
; #pragma unroll
;                     for (int n = 0; n < 2; ++n) { const int c = col0 + bj * HALF + n * 16; const f32x4 bs = *(const f32x4*)(b + c); const f32x4 v = bs + acc[ai][bj][m][n]; *(f32x4*)(o + c) = v;
;                         if (xb) { sq += (v[0] * v[0] + v[1] * v[1]) + (v[2] * v[2] + v[3] * v[3]); *(u32x2*)(xb + (size_t)row * DM + c) = (u32x2){cvt_pk_bf16(v[0], v[1]), cvt_pk_bf16(v[2], v[3])}; } }
;                 if (xb) { sq += __shfl_xor(sq, 16); sq += __shfl_xor(sq, 32); if (fq == 0) ssq[(size_t)row * 32 + u.pn * 4 + wc] = sq; }
;                 if (m & 1) asm volatile("" ::: "memory"); }
;     }
; template <class Epi, bool NARROW = false>
; __device__ __forceinline__ void gemm_phase(const Ctx cx, LAS unsigned char* lds, const Gemm g, const StaticOrder& S, const Epi& E) {
;     ...
;         if (wr == 0) PG8_BAR;
;         E(acc, cur, wr, wc, fr, fq);
;         if (!has_next) break;
;         { const float z = opaque_zero();
; #pragma unroll
;         for (int a = 0; a < 2; ++a)
; #pragma unroll
;             for (int b = 0; b < 2; ++b)
; #pragma unroll
;                 for (int m = 0; m < 4; ++m)
; #pragma unroll
;                     for (int n = 0; n < 2; ++n) acc[a][b][m][n] = (f32x4){z, z, z, z}; }
;         cur = nxt; cA = nA; cB = nB; ++ui;
;         if (wr == 1) PG8_BAR;
.Lepi_plain:
	s_waitcnt vmcnt(12)
	v_pk_add_f32 v[124:125], v[124:125], v[202:203]
	v_pk_add_f32 v[126:127], v[126:127], v[204:205]
	v_pk_add_f32 v[120:121], v[120:121], v[206:207]
	v_pk_add_f32 v[122:123], v[122:123], v[208:209]
	v_pk_add_f32 v[116:117], v[116:117], v[210:211]
	v_pk_add_f32 v[118:119], v[118:119], v[212:213]
	v_pk_add_f32 v[112:113], v[112:113], v[214:215]
	v_pk_add_f32 v[114:115], v[114:115], v[216:217]
	s_mov_b32 s4, s46
	s_mov_b32 s5, s47
	global_store_dwordx4 v140, v[124:127], s[4:5] offset:0
	global_store_dwordx4 v140, v[120:123], s[4:5] offset:64
	global_store_dwordx4 v140, v[116:119], s[4:5] offset:512
	global_store_dwordx4 v140, v[112:115], s[4:5] offset:576
	s_add_u32 s4, s44, 0x100000
	s_addc_u32 s5, s45, 0
	global_load_dwordx4 v[202:205], v140, s[4:5] offset:0
	global_load_dwordx4 v[206:209], v140, s[4:5] offset:64
	global_load_dwordx4 v[210:213], v140, s[4:5] offset:512
	global_load_dwordx4 v[214:217], v140, s[4:5] offset:576
	s_waitcnt vmcnt(16)
	v_pk_add_f32 v[108:109], v[108:109], v[218:219]
	v_pk_add_f32 v[110:111], v[110:111], v[220:221]
	v_pk_add_f32 v[104:105], v[104:105], v[222:223]
	v_pk_add_f32 v[106:107], v[106:107], v[224:225]
	v_pk_add_f32 v[100:101], v[100:101], v[226:227]
	v_pk_add_f32 v[102:103], v[102:103], v[228:229]
	v_pk_add_f32 v[96:97], v[96:97], v[230:231]
	v_pk_add_f32 v[98:99], v[98:99], v[232:233]
	s_add_u32 s4, s46, 0x20000
	s_addc_u32 s5, s47, 0
	global_store_dwordx4 v140, v[108:111], s[4:5] offset:0
	global_store_dwordx4 v140, v[104:107], s[4:5] offset:64
	global_store_dwordx4 v140, v[100:103], s[4:5] offset:512
	global_store_dwordx4 v140, v[96:99], s[4:5] offset:576
	s_add_u32 s4, s44, 0x120000
	s_addc_u32 s5, s45, 0
	global_load_dwordx4 v[218:221], v140, s[4:5] offset:0
	global_load_dwordx4 v[222:225], v140, s[4:5] offset:64
	global_load_dwordx4 v[226:229], v140, s[4:5] offset:512
	global_load_dwordx4 v[230:233], v140, s[4:5] offset:576
	s_waitcnt vmcnt(20)
	v_pk_add_f32 v[92:93], v[92:93], v[156:157]
	v_pk_add_f32 v[94:95], v[94:95], v[158:159]
	v_pk_add_f32 v[88:89], v[88:89], v[160:161]
	v_pk_add_f32 v[90:91], v[90:91], v[162:163]
	v_pk_add_f32 v[84:85], v[84:85], v[164:165]
	v_pk_add_f32 v[86:87], v[86:87], v[166:167]
	v_pk_add_f32 v[80:81], v[80:81], v[168:169]
	v_pk_add_f32 v[82:83], v[82:83], v[170:171]
	s_add_u32 s4, s46, 0x40000
	s_addc_u32 s5, s47, 0
	global_store_dwordx4 v140, v[92:95], s[4:5] offset:0
	global_store_dwordx4 v140, v[88:91], s[4:5] offset:64
	global_store_dwordx4 v140, v[84:87], s[4:5] offset:512
	global_store_dwordx4 v140, v[80:83], s[4:5] offset:576
	s_add_u32 s4, s44, 0x140000
	s_addc_u32 s5, s45, 0
	global_load_dwordx4 v[156:159], v140, s[4:5] offset:0
	global_load_dwordx4 v[160:163], v140, s[4:5] offset:64
	global_load_dwordx4 v[164:167], v140, s[4:5] offset:512
	global_load_dwordx4 v[168:171], v140, s[4:5] offset:576
	s_waitcnt vmcnt(24)
	v_pk_add_f32 v[76:77], v[76:77], v[144:145]
	v_pk_add_f32 v[78:79], v[78:79], v[146:147]
	v_pk_add_f32 v[72:73], v[72:73], v[148:149]
	v_pk_add_f32 v[74:75], v[74:75], v[150:151]
	v_pk_add_f32 v[68:69], v[68:69], v[172:173]
	v_pk_add_f32 v[70:71], v[70:71], v[174:175]
	v_pk_add_f32 v[64:65], v[64:65], v[176:177]
	v_pk_add_f32 v[66:67], v[66:67], v[178:179]
	s_add_u32 s4, s46, 0x60000
	s_addc_u32 s5, s47, 0
	global_store_dwordx4 v140, v[76:79], s[4:5] offset:0
	global_store_dwordx4 v140, v[72:75], s[4:5] offset:64
	global_store_dwordx4 v140, v[68:71], s[4:5] offset:512
	global_store_dwordx4 v140, v[64:67], s[4:5] offset:576
	s_add_u32 s4, s44, 0x160000
	s_addc_u32 s5, s45, 0
	global_load_dwordx4 v[144:147], v140, s[4:5] offset:0
	global_load_dwordx4 v[148:151], v140, s[4:5] offset:64
	global_load_dwordx4 v[172:175], v140, s[4:5] offset:512
	global_load_dwordx4 v[176:179], v140, s[4:5] offset:576
	s_waitcnt vmcnt(24)
	v_pk_add_f32 v[60:61], v[60:61], v[202:203]
	v_pk_add_f32 v[62:63], v[62:63], v[204:205]
	v_pk_add_f32 v[56:57], v[56:57], v[206:207]
	v_pk_add_f32 v[58:59], v[58:59], v[208:209]
	v_pk_add_f32 v[52:53], v[52:53], v[210:211]
	v_pk_add_f32 v[54:55], v[54:55], v[212:213]
	v_pk_add_f32 v[48:49], v[48:49], v[214:215]
	v_pk_add_f32 v[50:51], v[50:51], v[216:217]
	s_add_u32 s4, s46, 0x100000
	s_addc_u32 s5, s47, 0
	global_store_dwordx4 v140, v[60:63], s[4:5] offset:0
	global_store_dwordx4 v140, v[56:59], s[4:5] offset:64
	global_store_dwordx4 v140, v[52:55], s[4:5] offset:512
	global_store_dwordx4 v140, v[48:51], s[4:5] offset:576
	s_waitcnt vmcnt(20)
	v_pk_add_f32 v[44:45], v[44:45], v[218:219]
	v_pk_add_f32 v[46:47], v[46:47], v[220:221]
	v_pk_add_f32 v[40:41], v[40:41], v[222:223]
	v_pk_add_f32 v[42:43], v[42:43], v[224:225]
	v_pk_add_f32 v[36:37], v[36:37], v[226:227]
	v_pk_add_f32 v[38:39], v[38:39], v[228:229]
	v_pk_add_f32 v[32:33], v[32:33], v[230:231]
	v_pk_add_f32 v[34:35], v[34:35], v[232:233]
	s_add_u32 s4, s46, 0x120000
	s_addc_u32 s5, s47, 0
	global_store_dwordx4 v140, v[44:47], s[4:5] offset:0
	global_store_dwordx4 v140, v[40:43], s[4:5] offset:64
	global_store_dwordx4 v140, v[36:39], s[4:5] offset:512
	global_store_dwordx4 v140, v[32:35], s[4:5] offset:576
	s_waitcnt vmcnt(16)
	v_pk_add_f32 v[28:29], v[28:29], v[156:157]
	v_pk_add_f32 v[30:31], v[30:31], v[158:159]
	v_pk_add_f32 v[24:25], v[24:25], v[160:161]
	v_pk_add_f32 v[26:27], v[26:27], v[162:163]
	v_pk_add_f32 v[20:21], v[20:21], v[164:165]
	v_pk_add_f32 v[22:23], v[22:23], v[166:167]
	v_pk_add_f32 v[16:17], v[16:17], v[168:169]
	v_pk_add_f32 v[18:19], v[18:19], v[170:171]
	s_add_u32 s4, s46, 0x140000
	s_addc_u32 s5, s47, 0
	global_store_dwordx4 v140, v[28:31], s[4:5] offset:0
	global_store_dwordx4 v140, v[24:27], s[4:5] offset:64
	global_store_dwordx4 v140, v[20:23], s[4:5] offset:512
	global_store_dwordx4 v140, v[16:19], s[4:5] offset:576
	s_waitcnt vmcnt(12)
	v_pk_add_f32 v[12:13], v[12:13], v[144:145]
	v_pk_add_f32 v[14:15], v[14:15], v[146:147]
	v_pk_add_f32 v[8:9], v[8:9], v[148:149]
	v_pk_add_f32 v[10:11], v[10:11], v[150:151]
	v_pk_add_f32 v[4:5], v[4:5], v[172:173]
	v_pk_add_f32 v[6:7], v[6:7], v[174:175]
	v_pk_add_f32 v[0:1], v[0:1], v[176:177]
	v_pk_add_f32 v[2:3], v[2:3], v[178:179]
	s_add_u32 s4, s46, 0x160000
	s_addc_u32 s5, s47, 0
	global_store_dwordx4 v140, v[12:15], s[4:5] offset:0
	global_store_dwordx4 v140, v[8:11], s[4:5] offset:64
	global_store_dwordx4 v140, v[4:7], s[4:5] offset:512
	global_store_dwordx4 v140, v[0:3], s[4:5] offset:576
.Lepi_done:
.LBB0_162:
	s_and_b64 vcc, exec, s[8:9]
	s_mov_b64 s[4:5], -1
	s_cbranch_vccnz .LBB0_65
	s_andn2_b64 vcc, exec, s[36:37]
	v_mov_b32 v0, 0
	s_cbranch_vccnz .LBB0_64
	s_barrier
	s_branch .LBB0_64

; template <int MODE>
; __device__ __forceinline__ void partialSM(f32x16& p0, f32x16& p1, float& m_reg, float& mn, float& alpha, int rel0, int hi, bool need_mask) {
;     ...
;     float pmax = p0[0];
; #pragma unroll
;     for (int r = 1; r < 16; ++r) pmax = fmaxf(pmax, p0[r]);
; #pragma unroll
;     for (int r = 0; r < 16; ++r) pmax = fmaxf(pmax, p1[r]);
;     { auto rr = __builtin_amdgcn_permlane32_swap(__float_as_uint(pmax), __float_as_uint(pmax), false, false);
;       pmax = fmaxf(__uint_as_float(rr[0]), __uint_as_float(rr[1])); }
;     if (__builtin_expect(__all(pmax - m_reg <= THR / SCALE), 1)) { mn = m_reg; alpha = 1.f; }
;     else { mn = fmaxf(m_reg, pmax); alpha = __builtin_amdgcn_exp2f((m_reg - mn) * C); m_reg = mn; }
;     const float mnC = -mn * C;
; #pragma unroll
;     for (int r = 0; r < 16; ++r) p0[r] = fmaf(p0[r], C, mnC);
; #pragma unroll
;     for (int r = 0; r < 16; ++r) p1[r] = fmaf(p1[r], C, mnC);
; #pragma unroll
;     for (int r = 0; r < 16; ++r) p0[r] = __builtin_amdgcn_exp2f(p0[r]);
; template <int MODE>
; __device__ __forceinline__ void qkt(f32x16& p0, f32x16& p1, const int (&ka)[4], const int (&kra)[4], const bf16x8* qr) {
;     ...
;     if constexpr (MODE == 0) {
;         KRD(kb0[0], ka[0], 0); KRD(kb1[0], ka[0], 8192); KRD(kb0[1], ka[1], 0); KRD(kb1[1], ka[1], 8192);
;         KRD(kb0[2], ka[2], 0); KRD(kb1[2], ka[2], 8192); asm volatile("s_waitcnt lgkmcnt(4)" ::: "memory"); SBAR(); p0 = __builtin_amdgcn_mfma_f32_32x32x16_bf16(kb0[0], qr[0], zz, 0, 0, 0); p1 = __builtin_amdgcn_mfma_f32_32x32x16_bf16(kb1[0], qr[0], zz, 0, 0, 0);
;         KRD(kb0[0], ka[3], 0); KRD(kb1[0], ka[3], 8192); asm volatile("s_waitcnt lgkmcnt(4)" ::: "memory"); SBAR(); p0 = __builtin_amdgcn_mfma_f32_32x32x16_bf16(kb0[1], qr[1], p0, 0, 0, 0); p1 = __builtin_amdgcn_mfma_f32_32x32x16_bf16(kb1[1], qr[1], p1, 0, 0, 0);
;         KRD(kb0[1], ka[0], 128); KRD(kb1[1], ka[0], 8320); asm volatile("s_waitcnt lgkmcnt(4)" ::: "memory"); SBAR(); p0 = __builtin_amdgcn_mfma_f32_32x32x16_bf16(kb0[2], qr[2], p0, 0, 0, 0); p1 = __builtin_amdgcn_mfma_f32_32x32x16_bf16(kb1[2], qr[2], p1, 0, 0, 0);
;         KRD(kb0[2], ka[1], 128); KRD(kb1[2], ka[1], 8320); asm volatile("s_waitcnt lgkmcnt(4)" ::: "memory"); SBAR(); p0 = __builtin_amdgcn_mfma_f32_32x32x16_bf16(kb0[0], qr[3], p0, 0, 0, 0); p1 = __builtin_amdgcn_mfma_f32_32x32x16_bf16(kb1[0], qr[3], p1, 0, 0, 0);
.LBB0_285:
	v_and_b32_e32 v210, 63, v76
	v_lshlrev_b32_e32 v17, 4, v210
	s_and_b32 s0, s0, 0x3fffffc0
	v_lshlrev_b32_e32 v16, 3, v210
	v_and_b32_e32 v17, 0xc0, v17
	v_lshlrev_b32_e32 v18, 1, v210
	s_lshl_b32 s0, s0, 2
	v_and_or_b32 v17, v16, 24, v17
	v_and_b32_e32 v18, 32, v18
	v_and_b32_e32 v16, 0x100, v16
	s_add_i32 s23, s0, 0
	v_or3_b32 v16, v17, v18, v16
	v_lshlrev_b32_e32 v211, 4, v204
	v_lshlrev_b32_e32 v17, 4, v76
	s_add_i32 s0, 0, 0x1c000
	v_add_u32_e32 v212, 0, v16
	v_lshl_add_u32 v16, v203, 8, s5
	v_and_b32_e32 v17, 0x70, v17
	v_lshl_add_u32 v18, v203, 7, s0
	v_and_b32_e32 v19, 0x70, v77
	v_or_b32_e32 v20, 32, v211
	v_xad_u32 v215, v20, v17, v16
	v_xad_u32 v216, v20, v19, v18
	v_or_b32_e32 v20, 64, v211
	v_xad_u32 v217, v20, v17, v16
	v_xad_u32 v218, v20, v19, v18
	v_or_b32_e32 v20, 0x60, v211
	v_xad_u32 v213, v211, v17, v16
	v_xad_u32 v214, v211, v19, v18
	v_xad_u32 v219, v20, v17, v16
	v_xad_u32 v220, v20, v19, v18
	ds_read_b128 v[16:19], v213 offset:0
	ds_read_b128 v[20:23], v213 offset:0x2000
	ds_read_b128 v[70:73], v215 offset:0
	ds_read_b128 v[80:83], v215 offset:0x2000
	ds_read_b128 v[84:87], v217 offset:0
	ds_read_b128 v[88:91], v217 offset:0x2000
	s_waitcnt lgkmcnt(4)
	s_add_i32 s23, s23, 0x22000
	v_mov_b32_e32 v1, v0
	v_mov_b32_e32 v2, v0
	v_mov_b32_e32 v3, v0
	v_mov_b32_e32 v4, v0
	v_mov_b32_e32 v5, v0
	v_mov_b32_e32 v6, v0
	v_mov_b32_e32 v7, v0
	v_mov_b32_e32 v8, v0
	v_mov_b32_e32 v9, v0
	v_mov_b32_e32 v10, v0
	v_mov_b32_e32 v11, v0
	v_mov_b32_e32 v12, v0
	v_mov_b32_e32 v13, v0
	v_mov_b32_e32 v14, v0
	v_mov_b32_e32 v15, v0
	s_mov_b32 s42, 3
	s_mov_b32 s43, 1
	v_mfma_f32_32x32x16_bf16 v[32:47], v[16:19], v[96:99], 0
	ds_read_b128 v[92:95], v219 offset:0
	ds_read_b128 v[144:147], v219 offset:0x2000
	s_waitcnt lgkmcnt(4)
	v_mfma_f32_32x32x16_bf16 v[16:31], v[20:23], v[96:99], 0
	v_mfma_f32_32x32x16_bf16 v[32:47], v[70:73], v[100:103], v[32:47]
	ds_read_b128 v[70:73], v213 offset:0x80
	v_mfma_f32_32x32x16_bf16 v[16:31], v[80:83], v[100:103], v[16:31]
	ds_read_b128 v[80:83], v213 offset:0x2080
	s_waitcnt lgkmcnt(4)
	v_mfma_f32_32x32x16_bf16 v[32:47], v[84:87], v[104:107], v[32:47]
	ds_read_b128 v[84:87], v215 offset:0x80
	v_mfma_f32_32x32x16_bf16 v[16:31], v[88:91], v[104:107], v[16:31]
	ds_read_b128 v[88:91], v215 offset:0x2080
	s_waitcnt lgkmcnt(4)
	v_mfma_f32_32x32x16_bf16 v[32:47], v[92:95], v[108:111], v[32:47]
	ds_read_b128 v[92:95], v217 offset:0x80
	v_mfma_f32_32x32x16_bf16 v[16:31], v[144:147], v[108:111], v[16:31]
	ds_read_b128 v[144:147], v217 offset:0x2080
	s_waitcnt lgkmcnt(4)
	v_mfma_f32_32x32x16_bf16 v[32:47], v[70:73], v[112:115], v[32:47]
	ds_read_b128 v[70:73], v219 offset:0x80
	v_mfma_f32_32x32x16_bf16 v[16:31], v[80:83], v[112:115], v[16:31]
	ds_read_b128 v[80:83], v219 offset:0x2080
	s_waitcnt lgkmcnt(4)
	v_mfma_f32_32x32x16_bf16 v[32:47], v[84:87], v[116:119], v[32:47]
	ds_read_b128 v[84:87], v214 offset:0
	v_mfma_f32_32x32x16_bf16 v[16:31], v[88:91], v[116:119], v[16:31]
	ds_read_b128 v[88:91], v214 offset:0x1000
	s_waitcnt lgkmcnt(4)
	v_mfma_f32_32x32x16_bf16 v[32:47], v[92:95], v[120:123], v[32:47]
	ds_read_b128 v[92:95], v216 offset:0
	v_mfma_f32_32x32x16_bf16 v[16:31], v[144:147], v[120:123], v[16:31]
	ds_read_b128 v[144:147], v216 offset:0x1000
	s_waitcnt lgkmcnt(4)
	v_mfma_f32_32x32x16_bf16 v[32:47], v[70:73], v[124:127], v[32:47]
	ds_read_b128 v[70:73], v218 offset:0
	v_mfma_f32_32x32x16_bf16 v[16:31], v[80:83], v[124:127], v[16:31]
	ds_read_b128 v[80:83], v218 offset:0x1000
	s_waitcnt lgkmcnt(4)
	v_mfma_f32_32x32x16_bf16 v[32:47], v[84:87], v[128:131], v[32:47]
	ds_read_b128 v[84:87], v220 offset:0
	v_mfma_f32_32x32x16_bf16 v[16:31], v[88:91], v[128:131], v[16:31]
	ds_read_b128 v[88:91], v220 offset:0x1000
	s_waitcnt lgkmcnt(4)
	v_mfma_f32_32x32x16_bf16 v[32:47], v[92:95], v[136:139], v[32:47]
	s_waitcnt lgkmcnt(2)
	v_mfma_f32_32x32x16_bf16 v[16:31], v[144:147], v[136:139], v[16:31]
	v_mfma_f32_32x32x16_bf16 v[32:47], v[70:73], v[132:135], v[32:47]
	s_waitcnt lgkmcnt(0)
	v_mfma_f32_32x32x16_bf16 v[16:31], v[80:83], v[132:135], v[16:31]
	v_mfma_f32_32x32x16_bf16 v[32:47], v[84:87], v[140:143], v[32:47]
	s_barrier
	v_lshl_add_u32 v222, v203, 2, s23
	s_mov_b32 s45, 0
	s_mov_b32 s44, 0
	s_nop 7
	v_max_f32_e32 v70, v33, v33
	v_max_f32_e32 v71, v32, v32
	v_mfma_f32_32x32x16_bf16 v[16:31], v[88:91], v[140:143], v[16:31]
	v_max_f32_e32 v70, v71, v70
	v_max3_f32 v70, v70, v34, v35
	v_max3_f32 v70, v70, v36, v37
	v_max3_f32 v70, v70, v38, v39
	v_max3_f32 v70, v70, v40, v41
	v_max3_f32 v70, v70, v42, v43
	v_max3_f32 v70, v70, v44, v45
	v_max3_f32 v70, v70, v46, v47
	s_nop 3
	v_max3_f32 v70, v70, v16, v17
	v_max3_f32 v70, v70, v18, v19
	v_max3_f32 v70, v70, v20, v21
	v_max3_f32 v70, v70, v22, v23
	v_max3_f32 v70, v70, v24, v25
	v_max3_f32 v70, v70, v26, v27
	v_max3_f32 v70, v70, v28, v29
	v_max3_f32 v70, v70, v30, v31
	v_mov_b32_e32 v71, v70
	s_nop 1
	v_permlane32_swap_b32_e32 v70, v71
	v_max_f32_e32 v71, v71, v71
	v_max_f32_e32 v70, v70, v70
	v_max_f32_e32 v70, v70, v71
	v_add_f32_e32 v71, 0x46ea6000, v70
	v_cmp_ge_f32_e32 vcc, s1, v71
	s_cmp_eq_u64 vcc, exec
	s_cselect_b64 vcc, -1, 0
	v_max_f32_e32 v70, 0xc6ea6000, v70
	v_cndmask_b32_e32 v221, v70, v193, vcc
	v_mul_f32_e32 v71, 0xbdd53b94, v221
	v_fmamk_f32 v32, v32, 0x3dd53b94, v71
	v_fmamk_f32 v33, v33, 0x3dd53b94, v71
	v_fmamk_f32 v34, v34, 0x3dd53b94, v71
	v_fmamk_f32 v35, v35, 0x3dd53b94, v71
	v_fmamk_f32 v36, v36, 0x3dd53b94, v71
	v_fmamk_f32 v37, v37, 0x3dd53b94, v71
	v_fmamk_f32 v38, v38, 0x3dd53b94, v71
	v_fmamk_f32 v39, v39, 0x3dd53b94, v71
	v_fmamk_f32 v40, v40, 0x3dd53b94, v71
	v_fmamk_f32 v41, v41, 0x3dd53b94, v71
	v_fmamk_f32 v42, v42, 0x3dd53b94, v71
; #define SBAR() __builtin_amdgcn_sched_barrier(0)
; #define SLOAD(k0) SLOADX(sg, k0)
; #define KADDR(slot) do { _Pragma("unroll") for (int i = 0; i < 4; ++i) { ka[i] = kb_[i] + (slot) * SHM_K; kra[i] = krb_[i] + (slot) * SHM_KR; } } while (0)
; __device__ __forceinline__ void finishSM(f32x16& p0, f32x16& p1, float alpha, float& l_reg, bf16x8& pa0, bf16x8& pa1, bf16x8& pa2, bf16x8& pa3) {
; #pragma unroll
;     for (int r = 0; r < 16; ++r) p1[r] = __builtin_amdgcn_exp2f(p1[r]);
;     float ps = 0;
; #pragma unroll
;     for (int r = 0; r < 16; ++r) ps += p0[r];
; #pragma unroll
;     for (int r = 0; r < 16; ++r) ps += p1[r];
;     { auto rr = __builtin_amdgcn_permlane32_swap(__float_as_uint(ps), __float_as_uint(ps), false, false);
;       ps = __uint_as_float(rr[0]) + __uint_as_float(rr[1]); }
;     l_reg = l_reg * alpha + ps;
;     ...
;     PK4(p0, 0, pa0); PK4(p0, 8, pa1); PK4(p1, 0, pa2); PK4(p1, 8, pa3);
; template <int MODE> ...
;     ...
;     if (2 < NT) { asm volatile("s_waitcnt vmcnt(0)" ::: "memory"); SWRITEX(sg, 2, 2); } if (3 < NT) SLOAD(3 * 64);
;     __syncthreads();
;     int ks = 1, vp = 0, kw = 0, vw = 3;
;     for (int j = 1; j < NT; ++j) {
;         KADDR(ks); SBAR();
;         if constexpr (MODE != 0) { const bool ap = ACT(j - 1), ac = ACT(j); VFr fa; if (ap) vread<0>(fa, vb0 + vp * SHM_V); if (ac) qkt<MODE>(p0, p1, ka, kra, qr); if (ap) pv_pipe(o, vb0 + vp * SHM_V, fa, pa0, pa1, pa2, pa3); }
;         else { qkt<MODE>(p0, p1, ka, kra, qr); pv_d0(o, vb0 + vp * SHM_V, pa0, pa1, pa2, pa3); }
	v_fmamk_f32 v43, v43, 0x3dd53b94, v71
	v_fmamk_f32 v44, v44, 0x3dd53b94, v71
	v_fmamk_f32 v45, v45, 0x3dd53b94, v71
	v_fmamk_f32 v46, v46, 0x3dd53b94, v71
	v_fmamk_f32 v47, v47, 0x3dd53b94, v71
	v_fmamk_f32 v16, v16, 0x3dd53b94, v71
	v_fmamk_f32 v17, v17, 0x3dd53b94, v71
	v_fmamk_f32 v18, v18, 0x3dd53b94, v71
	v_fmamk_f32 v19, v19, 0x3dd53b94, v71
	v_fmamk_f32 v20, v20, 0x3dd53b94, v71
	v_fmamk_f32 v21, v21, 0x3dd53b94, v71
	v_fmamk_f32 v22, v22, 0x3dd53b94, v71
	v_fmamk_f32 v23, v23, 0x3dd53b94, v71
	v_fmamk_f32 v24, v24, 0x3dd53b94, v71
	v_fmamk_f32 v25, v25, 0x3dd53b94, v71
	v_fmamk_f32 v26, v26, 0x3dd53b94, v71
	v_fmamk_f32 v27, v27, 0x3dd53b94, v71
	v_fmamk_f32 v28, v28, 0x3dd53b94, v71
	v_fmamk_f32 v29, v29, 0x3dd53b94, v71
	v_fmamk_f32 v30, v30, 0x3dd53b94, v71
	v_fmac_f32_e32 v71, 0x3dd53b94, v31
	v_exp_f32_e32 v31, v32
	v_exp_f32_e32 v32, v33
	v_exp_f32_e32 v33, v34
	v_exp_f32_e32 v34, v35
	v_exp_f32_e32 v35, v36
	v_exp_f32_e32 v36, v37
	v_exp_f32_e32 v37, v38
	v_exp_f32_e32 v38, v39
	v_exp_f32_e32 v39, v40
	v_exp_f32_e32 v40, v41
	v_exp_f32_e32 v41, v42
	v_exp_f32_e32 v42, v43
	v_exp_f32_e32 v43, v44
	v_exp_f32_e32 v44, v45
	v_exp_f32_e32 v45, v46
	v_exp_f32_e32 v46, v47
	v_exp_f32_e32 v47, v71
	v_add_f32_e32 v71, 0, v31
	v_add_f32_e32 v71, v32, v71
	v_add_f32_e32 v71, v33, v71
	v_add_f32_e32 v71, v34, v71
	v_add_f32_e32 v71, v35, v71
	v_add_f32_e32 v71, v36, v71
	v_add_f32_e32 v71, v37, v71
	v_add_f32_e32 v71, v38, v71
	v_add_f32_e32 v71, v39, v71
	v_add_f32_e32 v71, v40, v71
	v_add_f32_e32 v71, v41, v71
	v_add_f32_e32 v71, v42, v71
	v_exp_f32_e32 v16, v16
	v_add_f32_e32 v71, v43, v71
	v_add_f32_e32 v71, v44, v71
	v_exp_f32_e32 v17, v17
	v_add_f32_e32 v71, v45, v71
	v_exp_f32_e32 v18, v18
	v_add_f32_e32 v71, v46, v71
	s_add_i32 s0, 0, 0x18000
	v_exp_f32_e32 v19, v19
	v_add_f32_e32 v71, v16, v71
	v_cvt_pk_bf16_f32 v164, v31, v32
	v_cvt_pk_bf16_f32 v165, v33, v34
	v_cvt_pk_bf16_f32 v166, v35, v36
	v_cvt_pk_bf16_f32 v167, v37, v38
	v_cvt_pk_bf16_f32 v168, v39, v40
	v_cvt_pk_bf16_f32 v169, v41, v42
	v_cvt_pk_bf16_f32 v170, v43, v44
	v_cvt_pk_bf16_f32 v171, v45, v46
	v_cvt_pk_bf16_f32 v172, v16, v17
	v_add_u32_e32 v16, s0, v207
	v_exp_f32_e32 v20, v20
	v_exp_f32_e32 v21, v21
	v_exp_f32_e32 v22, v22
	v_exp_f32_e32 v23, v23
	v_exp_f32_e32 v24, v24
	v_exp_f32_e32 v25, v25
	v_exp_f32_e32 v26, v26
	v_exp_f32_e32 v27, v27
	v_exp_f32_e32 v28, v28
	v_exp_f32_e32 v29, v29
	v_exp_f32_e32 v30, v30
	v_cvt_pk_bf16_f32 v173, v18, v19
	v_cvt_pk_bf16_f32 v174, v20, v21
	v_cvt_pk_bf16_f32 v175, v22, v23
	v_cvt_pk_bf16_f32 v176, v24, v25
	v_cvt_pk_bf16_f32 v177, v26, v27
	v_cvt_pk_bf16_f32 v178, v28, v29
	v_cvt_pk_bf16_f32 v179, v30, v47
	s_waitcnt vmcnt(0)
	s_waitcnt vmcnt(4)
	ds_write_b128 v74, v[48:51] offset:32768
	s_waitcnt vmcnt(3)
	ds_write_b128 v75, v[60:63] offset:32768
	s_waitcnt vmcnt(2)
	ds_write_b128 v16, v[52:55]
	v_add_u32_e32 v16, s0, v208
	v_add_f32_e32 v71, v17, v71
	s_waitcnt vmcnt(1)
	ds_write_b128 v16, v[56:59]
	v_add_u32_e32 v16, 0x20000, v78
	v_add_f32_e32 v71, v18, v71
	s_waitcnt vmcnt(0)
	ds_write_b128 v16, v[64:67]
	v_lshlrev_b64 v[16:17], 1, v[68:69]
	s_and_b64 s[4:5], s[8:9], exec
	v_add_f32_e32 v71, v19, v71
	v_lshl_add_u64 v[18:19], s[6:7], 0, v[16:17]
	s_movk_i32 s0, 0x6000
	s_cselect_b32 s4, s84, 0x180000
	v_add_co_u32_e64 v18, s[6:7], s0, v18
	s_add_u32 s4, s18, s4
	v_add_f32_e32 v71, v20, v71
	v_addc_co_u32_e64 v19, s[6:7], 0, v19, s[6:7]
	s_addc_u32 s5, s19, 0
	v_add_f32_e32 v71, v21, v71
	global_load_dwordx4 v[144:147], v[18:19], off
	v_lshl_add_u64 v[18:19], v[182:183], 1, s[4:5]
	v_lshl_add_u64 v[20:21], v[180:181], 1, s[4:5]
	global_load_dwordx4 v[148:151], v[18:19], off
	global_load_dwordx4 v[152:155], v[20:21], off
	global_load_dwordx4 v[160:163], v[18:19], off offset:256
	global_load_dwordx4 v[156:159], v[20:21], off offset:256
	v_add_f32_e32 v71, v22, v71
	v_add_f32_e32 v71, v23, v71
	v_add_f32_e32 v71, v24, v71
	v_add_f32_e32 v71, v25, v71
	v_add_f32_e32 v71, v26, v71
	v_add_f32_e32 v71, v27, v71
	v_sub_f32_e32 v19, 0xc6ea6000, v70
	v_add_f32_e32 v71, v28, v71
	v_mul_f32_e32 v19, 0x3dd53b94, v19
	v_add_f32_e32 v71, v29, v71
	v_exp_f32_e32 v19, v19
	v_add_f32_e32 v71, v30, v71
	v_add_f32_e32 v71, v47, v71
	s_and_b64 s[4:5], s[8:9], exec
	v_mov_b32_e32 v72, v71
	s_cselect_b32 s33, 10, 12
	s_add_i32 s40, s39, -1
	v_permlane32_swap_b32_e32 v71, v72
	v_mul_f32_e32 v19, 0, v19
	s_add_u32 s4, s34, s20
	v_add_f32_e32 v18, v71, v72
	v_cndmask_b32_e64 v19, v19, 0, vcc
	s_addc_u32 s5, s35, s21
	v_add_f32_e32 v223, v18, v19
	v_lshl_add_u64 v[184:185], s[4:5], 0, v[16:17]
	v_mov_b64_e32 v[62:63], v[14:15]
	v_mov_b64_e32 v[46:47], v[14:15]
	v_mov_b64_e32 v[30:31], v[14:15]
	v_permlane32_swap_b32_e32 v164, v166
	v_permlane32_swap_b32_e32 v165, v167
	v_permlane32_swap_b32_e32 v168, v170
	v_permlane32_swap_b32_e32 v169, v171
	v_permlane32_swap_b32_e32 v172, v174
	v_permlane32_swap_b32_e32 v173, v175
	v_permlane32_swap_b32_e32 v176, v178
	v_permlane32_swap_b32_e32 v177, v179
	s_mov_b32 s0, 0
	v_cmp_gt_u32_e64 s[6:7], 32, v210
	s_mov_b64 s[20:21], 0x100
	v_mov_b64_e32 v[60:61], v[12:13]
	v_mov_b64_e32 v[58:59], v[10:11]
	v_mov_b64_e32 v[56:57], v[8:9]
	v_mov_b64_e32 v[54:55], v[6:7]
	v_mov_b64_e32 v[52:53], v[4:5]
	v_mov_b64_e32 v[50:51], v[2:3]
	v_mov_b64_e32 v[48:49], v[0:1]
	v_mov_b64_e32 v[44:45], v[12:13]
	v_mov_b64_e32 v[42:43], v[10:11]
	v_mov_b64_e32 v[40:41], v[8:9]
	v_mov_b64_e32 v[38:39], v[6:7]
	v_mov_b64_e32 v[36:37], v[4:5]
	v_mov_b64_e32 v[34:35], v[2:3]
	v_mov_b64_e32 v[32:33], v[0:1]
	v_mov_b64_e32 v[28:29], v[12:13]
	v_mov_b64_e32 v[26:27], v[10:11]
	v_mov_b64_e32 v[24:25], v[8:9]
	v_mov_b64_e32 v[22:23], v[6:7]
	v_mov_b64_e32 v[20:21], v[4:5]
	v_mov_b64_e32 v[18:19], v[2:3]
	v_mov_b64_e32 v[16:17], v[0:1]
	s_lshl_b32 s4, s43, 14
	s_lshl_b32 s5, s43, 13
	v_add_u32_e32 v248, s4, v213
	v_add_u32_e32 v249, s5, v214
	v_add_u32_e32 v250, s4, v215
	v_add_u32_e32 v251, s5, v216
	v_add_u32_e32 v252, s4, v217
	v_add_u32_e32 v253, s5, v218
	v_add_u32_e32 v188, s4, v219
	v_add_u32_e32 v191, s5, v220
	ds_read_b128 v[192:195], v248 offset:0x0
	ds_read_b128 v[196:199], v248 offset:0x2000
	ds_read_b128 v[224:227], v250 offset:0x0
	ds_read_b128 v[228:231], v250 offset:0x2000
	ds_read_b128 v[232:235], v252 offset:0x0
	ds_read_b128 v[236:239], v252 offset:0x2000
	ds_read_b128 v[240:243], v188 offset:0x0
	ds_read_b128 v[244:247], v188 offset:0x2000
	s_waitcnt lgkmcnt(8)
	s_barrier
; #define SBAR() __builtin_amdgcn_sched_barrier(0)
; #define KRD(dst, addr, off) asm volatile("ds_read_b128 %0, %1 offset:%2" : "=&v"(dst) : "v"(addr), "i"(off) : "memory")
; template <int MODE>
; __device__ __forceinline__ void qkt(f32x16& p0, f32x16& p1, const int (&ka)[4], const int (&kra)[4], const bf16x8* qr) {
;     ...
;     if constexpr (MODE == 0) {
;         KRD(kb0[0], ka[0], 0); KRD(kb1[0], ka[0], 8192); KRD(kb0[1], ka[1], 0); KRD(kb1[1], ka[1], 8192);
;         KRD(kb0[2], ka[2], 0); KRD(kb1[2], ka[2], 8192); asm volatile("s_waitcnt lgkmcnt(4)" ::: "memory"); SBAR(); p0 = __builtin_amdgcn_mfma_f32_32x32x16_bf16(kb0[0], qr[0], zz, 0, 0, 0); p1 = __builtin_amdgcn_mfma_f32_32x32x16_bf16(kb1[0], qr[0], zz, 0, 0, 0);
;         KRD(kb0[0], ka[3], 0); KRD(kb1[0], ka[3], 8192); asm volatile("s_waitcnt lgkmcnt(4)" ::: "memory"); SBAR(); p0 = __builtin_amdgcn_mfma_f32_32x32x16_bf16(kb0[1], qr[1], p0, 0, 0, 0); p1 = __builtin_amdgcn_mfma_f32_32x32x16_bf16(kb1[1], qr[1], p1, 0, 0, 0);
;         KRD(kb0[1], ka[0], 128); KRD(kb1[1], ka[0], 8320); asm volatile("s_waitcnt lgkmcnt(4)" ::: "memory"); SBAR(); p0 = __builtin_amdgcn_mfma_f32_32x32x16_bf16(kb0[2], qr[2], p0, 0, 0, 0); p1 = __builtin_amdgcn_mfma_f32_32x32x16_bf16(kb1[2], qr[2], p1, 0, 0, 0);
;         KRD(kb0[2], ka[1], 128); KRD(kb1[2], ka[1], 8320); asm volatile("s_waitcnt lgkmcnt(4)" ::: "memory"); SBAR(); p0 = __builtin_amdgcn_mfma_f32_32x32x16_bf16(kb0[0], qr[3], p0, 0, 0, 0); p1 = __builtin_amdgcn_mfma_f32_32x32x16_bf16(kb1[0], qr[3], p1, 0, 0, 0);
;         KRD(kb0[0], ka[2], 128); KRD(kb1[0], ka[2], 8320); asm volatile("s_waitcnt lgkmcnt(4)" ::: "memory"); SBAR(); p0 = __builtin_amdgcn_mfma_f32_32x32x16_bf16(kb0[1], qr[4], p0, 0, 0, 0); p1 = __builtin_amdgcn_mfma_f32_32x32x16_bf16(kb1[1], qr[4], p1, 0, 0, 0);
;         KRD(kb0[1], ka[3], 128); KRD(kb1[1], ka[3], 8320); asm volatile("s_waitcnt lgkmcnt(4)" ::: "memory"); SBAR(); p0 = __builtin_amdgcn_mfma_f32_32x32x16_bf16(kb0[2], qr[5], p0, 0, 0, 0); p1 = __builtin_amdgcn_mfma_f32_32x32x16_bf16(kb1[2], qr[5], p1, 0, 0, 0);
;         KRD(kb0[2], kra[0], 0); KRD(kb1[2], kra[0], 4096); asm volatile("s_waitcnt lgkmcnt(4)" ::: "memory"); SBAR(); p0 = __builtin_amdgcn_mfma_f32_32x32x16_bf16(kb0[0], qr[6], p0, 0, 0, 0); p1 = __builtin_amdgcn_mfma_f32_32x32x16_bf16(kb1[0], qr[6], p1, 0, 0, 0);
.LBB0_286:
	s_waitcnt lgkmcnt(6)
	v_mfma_f32_32x32x16_bf16 v[80:95], v[192:195], v[96:99], 0
	ds_read_b128 v[192:195], v248 offset:0x80
	v_mfma_f32_32x32x16_bf16 v[64:79], v[196:199], v[96:99], 0
	ds_read_b128 v[196:199], v248 offset:0x2080
	s_waitcnt lgkmcnt(6)
	v_mfma_f32_32x32x16_bf16 v[80:95], v[224:227], v[100:103], v[80:95]
	ds_read_b128 v[224:227], v250 offset:0x80
	v_mfma_f32_32x32x16_bf16 v[64:79], v[228:231], v[100:103], v[64:79]
	ds_read_b128 v[228:231], v250 offset:0x2080
	s_waitcnt lgkmcnt(6)
	v_mfma_f32_32x32x16_bf16 v[80:95], v[232:235], v[104:107], v[80:95]
	ds_read_b128 v[232:235], v252 offset:0x80
	v_mfma_f32_32x32x16_bf16 v[64:79], v[236:239], v[104:107], v[64:79]
	ds_read_b128 v[236:239], v252 offset:0x2080
	s_waitcnt lgkmcnt(6)
	v_mfma_f32_32x32x16_bf16 v[80:95], v[240:243], v[108:111], v[80:95]
	ds_read_b128 v[240:243], v188 offset:0x80
	v_mfma_f32_32x32x16_bf16 v[64:79], v[244:247], v[108:111], v[64:79]
	ds_read_b128 v[244:247], v188 offset:0x2080
	s_waitcnt lgkmcnt(6)
	v_mfma_f32_32x32x16_bf16 v[80:95], v[192:195], v[112:115], v[80:95]
	ds_read_b128 v[192:195], v249 offset:0x0
	v_mfma_f32_32x32x16_bf16 v[64:79], v[196:199], v[112:115], v[64:79]
	ds_read_b128 v[196:199], v249 offset:0x1000
	s_waitcnt lgkmcnt(6)
	v_mfma_f32_32x32x16_bf16 v[80:95], v[224:227], v[116:119], v[80:95]
	ds_read_b128 v[224:227], v251 offset:0x0
	v_mfma_f32_32x32x16_bf16 v[64:79], v[228:231], v[116:119], v[64:79]
	ds_read_b128 v[228:231], v251 offset:0x1000
	s_waitcnt lgkmcnt(6)
	v_mfma_f32_32x32x16_bf16 v[80:95], v[232:235], v[120:123], v[80:95]
	ds_read_b128 v[232:235], v253 offset:0x0
	v_mfma_f32_32x32x16_bf16 v[64:79], v[236:239], v[120:123], v[64:79]
	ds_read_b128 v[236:239], v253 offset:0x1000
	s_waitcnt lgkmcnt(6)
	v_mfma_f32_32x32x16_bf16 v[80:95], v[240:243], v[124:127], v[80:95]
	ds_read_b128 v[240:243], v191 offset:0x0
	v_mfma_f32_32x32x16_bf16 v[64:79], v[244:247], v[124:127], v[64:79]
	ds_read_b128 v[244:247], v191 offset:0x1000
	v_lshl_add_u32 v200, s44, 14, v212
	s_waitcnt lgkmcnt(6)
	v_mfma_f32_32x32x16_bf16 v[80:95], v[192:195], v[128:131], v[80:95]
	ds_read_b64_tr_b16 v[192:193], v200 offset:0x0
	ds_read_b64_tr_b16 v[194:195], v200 offset:0x800
	v_mfma_f32_32x32x16_bf16 v[64:79], v[196:199], v[128:131], v[64:79]
	ds_read_b64_tr_b16 v[196:197], v200 offset:0x1000
	ds_read_b64_tr_b16 v[198:199], v200 offset:0x1800
	s_waitcnt lgkmcnt(8)
	v_mfma_f32_32x32x16_bf16 v[80:95], v[224:227], v[136:139], v[80:95]
	ds_read_b64_tr_b16 v[224:225], v200 offset:0x2000
	ds_read_b64_tr_b16 v[226:227], v200 offset:0x2800
	v_mfma_f32_32x32x16_bf16 v[64:79], v[228:231], v[136:139], v[64:79]
	ds_read_b64_tr_b16 v[228:229], v200 offset:0x3000
	ds_read_b64_tr_b16 v[230:231], v200 offset:0x3800
	s_waitcnt lgkmcnt(10)
	v_mfma_f32_32x32x16_bf16 v[80:95], v[232:235], v[132:135], v[80:95]
	ds_read_b64_tr_b16 v[232:233], v200 offset:0x200
	ds_read_b64_tr_b16 v[234:235], v200 offset:0xa00
	v_mfma_f32_32x32x16_bf16 v[64:79], v[236:239], v[132:135], v[64:79]
	ds_read_b64_tr_b16 v[236:237], v200 offset:0x1200
	ds_read_b64_tr_b16 v[238:239], v200 offset:0x1a00
	s_waitcnt lgkmcnt(12)
	v_mfma_f32_32x32x16_bf16 v[80:95], v[240:243], v[140:143], v[80:95]
	ds_read_b64_tr_b16 v[240:241], v200 offset:0x2200
	ds_read_b64_tr_b16 v[242:243], v200 offset:0x2a00
	v_mfma_f32_32x32x16_bf16 v[64:79], v[244:247], v[140:143], v[64:79]
	s_waitcnt lgkmcnt(12)
	v_mfma_f32_32x32x16_bf16 v[0:15], v[164:167], v[192:195], v[0:15]
	ds_read_b64_tr_b16 v[244:245], v200 offset:0x3200
	ds_read_b64_tr_b16 v[246:247], v200 offset:0x3a00
	s_waitcnt lgkmcnt(12)
	v_mfma_f32_32x32x16_bf16 v[0:15], v[168:171], v[196:199], v[0:15]
	ds_read_b64_tr_b16 v[192:193], v200 offset:0x400
	ds_read_b64_tr_b16 v[194:195], v200 offset:0xc00
	s_waitcnt lgkmcnt(12)
	v_mfma_f32_32x32x16_bf16 v[0:15], v[172:175], v[224:227], v[0:15]
	ds_read_b64_tr_b16 v[196:197], v200 offset:0x1400
	ds_read_b64_tr_b16 v[198:199], v200 offset:0x1c00
	s_waitcnt lgkmcnt(12)
	v_mfma_f32_32x32x16_bf16 v[0:15], v[176:179], v[228:231], v[0:15]
	ds_read_b64_tr_b16 v[224:225], v200 offset:0x2400
	ds_read_b64_tr_b16 v[226:227], v200 offset:0x2c00
	s_waitcnt lgkmcnt(12)
	v_mfma_f32_32x32x16_bf16 v[48:63], v[164:167], v[232:235], v[48:63]
	ds_read_b64_tr_b16 v[228:229], v200 offset:0x3400
	ds_read_b64_tr_b16 v[230:231], v200 offset:0x3c00
	s_waitcnt lgkmcnt(12)
	v_mfma_f32_32x32x16_bf16 v[48:63], v[168:171], v[236:239], v[48:63]
	ds_read_b64_tr_b16 v[232:233], v200 offset:0x600
	ds_read_b64_tr_b16 v[234:235], v200 offset:0xe00
	v_max_f32_e32 v248, v81, v81
	v_max_f32_e32 v250, v80, v80
	v_max_f32_e32 v248, v250, v248
	s_waitcnt lgkmcnt(12)
	v_mfma_f32_32x32x16_bf16 v[48:63], v[172:175], v[240:243], v[48:63]
	ds_read_b64_tr_b16 v[236:237], v200 offset:0x1600
	ds_read_b64_tr_b16 v[238:239], v200 offset:0x1e00
	v_max3_f32 v248, v248, v82, v83
	v_max3_f32 v248, v248, v84, v85
	v_max3_f32 v248, v248, v86, v87
	s_waitcnt lgkmcnt(12)
	v_mfma_f32_32x32x16_bf16 v[48:63], v[176:179], v[244:247], v[48:63]
	ds_read_b64_tr_b16 v[240:241], v200 offset:0x2600
	ds_read_b64_tr_b16 v[242:243], v200 offset:0x2e00
	v_max3_f32 v248, v248, v88, v89
	v_max3_f32 v248, v248, v90, v91
	v_max3_f32 v248, v248, v92, v93
	s_waitcnt lgkmcnt(12)
	v_mfma_f32_32x32x16_bf16 v[32:47], v[164:167], v[192:195], v[32:47]
	ds_read_b64_tr_b16 v[244:245], v200 offset:0x3600
	ds_read_b64_tr_b16 v[246:247], v200 offset:0x3e00
	v_max3_f32 v248, v248, v94, v95
	v_max3_f32 v248, v248, v64, v65
	v_max3_f32 v248, v248, v66, v67
	s_waitcnt lgkmcnt(12)
	v_mfma_f32_32x32x16_bf16 v[32:47], v[168:171], v[196:199], v[32:47]
	v_max3_f32 v248, v248, v68, v69
	v_max3_f32 v248, v248, v70, v71
	v_max3_f32 v248, v248, v72, v73
	s_waitcnt lgkmcnt(10)
	v_mfma_f32_32x32x16_bf16 v[32:47], v[172:175], v[224:227], v[32:47]
	v_max3_f32 v248, v248, v74, v75
	v_max3_f32 v248, v248, v76, v77
	v_max3_f32 v248, v248, v78, v79
	s_waitcnt lgkmcnt(8)
	v_mfma_f32_32x32x16_bf16 v[32:47], v[176:179], v[228:231], v[32:47]
	s_waitcnt lgkmcnt(6)
	v_mfma_f32_32x32x16_bf16 v[16:31], v[164:167], v[232:235], v[16:31]
	s_waitcnt lgkmcnt(4)
	v_mfma_f32_32x32x16_bf16 v[16:31], v[168:171], v[236:239], v[16:31]
	v_mov_b32_e32 v164, v248
	v_mov_b32_e32 v165, v248
	s_nop 1
	v_permlane32_swap_b32_e32 v164, v165
	v_max_f32_e32 v165, v165, v165
	v_max_f32_e32 v164, v164, v164
	s_waitcnt lgkmcnt(2)
	v_mfma_f32_32x32x16_bf16 v[16:31], v[172:175], v[240:243], v[16:31]
	v_max_f32_e32 v164, v164, v165
	v_sub_f32_e32 v165, v164, v221
	v_cmp_ge_f32_e32 vcc, s1, v165
	v_max_f32_e32 v165, v221, v221
	v_max_f32_e32 v164, v165, v164
	v_sub_f32_e32 v165, v221, v164
	s_waitcnt lgkmcnt(0)
	v_mfma_f32_32x32x16_bf16 v[16:31], v[176:179], v[244:247], v[16:31]
	v_mul_f32_e32 v165, 0x3dd53b94, v165
	v_exp_f32_e32 v165, v165
	s_cmp_eq_u64 vcc, exec
	s_cselect_b64 s[8:9], -1, 0
	v_cndmask_b32_e64 v224, v165, 1.0, s[8:9]
	v_cmp_gt_f32_e32 vcc, 1.0, v224
	s_barrier
; #define RESC(a) do { if (__any((a) < 1.f)) { if (hi == 0) al_l[r32] = (a); asm volatile("s_waitcnt lgkmcnt(0)" ::: "memory"); \
;     _Pragma("unroll") for (int d = 0; d < 4; ++d) _Pragma("unroll") for (int r = 0; r < 16; ++r) o[d][r] *= al_l[crow(r, hi)]; } } while (0)
; template <int MODE> ...
;     ...
;         if (ACT(j)) { partialSM<MODE>(p0, p1, m_reg, mn, al, REL0(j), hi, NEEDM(j)); RESC(al); finishSM(p0, p1, al, l_reg, pa0, pa1, pa2, pa3); }
	s_cbranch_vccz .LBB0_290
	s_and_saveexec_b64 s[4:5], s[6:7]
	ds_write_b32 v222, v224 offset:128
	s_or_b64 exec, exec, s[4:5]
	s_waitcnt lgkmcnt(0)
	v_add_u32_e32 v165, s23, v211
	ds_read_b128 v[166:169], v165 offset:224
	ds_read_b128 v[170:173], v165 offset:192
	ds_read_b128 v[174:177], v165 offset:160
	ds_read_b128 v[226:229], v165 offset:128
	s_waitcnt lgkmcnt(3)
	v_pk_mul_f32 v[12:13], v[12:13], v[166:167]
	s_waitcnt lgkmcnt(2)
	v_pk_mul_f32 v[8:9], v[8:9], v[170:171]
	s_waitcnt lgkmcnt(1)
	v_pk_mul_f32 v[4:5], v[4:5], v[174:175]
	v_pk_mul_f32 v[14:15], v[14:15], v[168:169]
	v_pk_mul_f32 v[10:11], v[10:11], v[172:173]
	v_pk_mul_f32 v[6:7], v[6:7], v[176:177]
	s_waitcnt lgkmcnt(0)
	v_pk_mul_f32 v[2:3], v[2:3], v[228:229]
	v_pk_mul_f32 v[0:1], v[0:1], v[226:227]
	v_pk_mul_f32 v[60:61], v[60:61], v[166:167]
	v_pk_mul_f32 v[56:57], v[56:57], v[170:171]
	v_pk_mul_f32 v[52:53], v[52:53], v[174:175]
	v_pk_mul_f32 v[62:63], v[62:63], v[168:169]
	v_pk_mul_f32 v[58:59], v[58:59], v[172:173]
	v_pk_mul_f32 v[54:55], v[54:55], v[176:177]
	v_pk_mul_f32 v[50:51], v[50:51], v[228:229]
	v_pk_mul_f32 v[48:49], v[48:49], v[226:227]
	v_pk_mul_f32 v[44:45], v[44:45], v[166:167]
	v_pk_mul_f32 v[40:41], v[40:41], v[170:171]
	v_pk_mul_f32 v[36:37], v[36:37], v[174:175]
	v_pk_mul_f32 v[46:47], v[46:47], v[168:169]
	v_pk_mul_f32 v[42:43], v[42:43], v[172:173]
	v_pk_mul_f32 v[38:39], v[38:39], v[176:177]
	v_pk_mul_f32 v[34:35], v[34:35], v[228:229]
	v_pk_mul_f32 v[32:33], v[32:33], v[226:227]
	v_pk_mul_f32 v[28:29], v[28:29], v[166:167]
	v_pk_mul_f32 v[24:25], v[24:25], v[170:171]
	v_pk_mul_f32 v[20:21], v[20:21], v[174:175]
	v_pk_mul_f32 v[30:31], v[30:31], v[168:169]
	v_pk_mul_f32 v[26:27], v[26:27], v[172:173]
	v_pk_mul_f32 v[22:23], v[22:23], v[176:177]
	v_pk_mul_f32 v[18:19], v[18:19], v[228:229]
	v_pk_mul_f32 v[16:17], v[16:17], v[226:227]

; #define SBAR() __builtin_amdgcn_sched_barrier(0)
; #define SLOAD(k0) SLOADX(sg, k0)
; #define RESC(a) do { if (__any((a) < 1.f)) { if (hi == 0) al_l[r32] = (a); asm volatile("s_waitcnt lgkmcnt(0)" ::: "memory"); \
;     _Pragma("unroll") for (int d = 0; d < 4; ++d) _Pragma("unroll") for (int r = 0; r < 16; ++r) o[d][r] *= al_l[crow(r, hi)]; } } while (0)
; #define KADDR(slot) do { _Pragma("unroll") for (int i = 0; i < 4; ++i) { ka[i] = kb_[i] + (slot) * SHM_K; kra[i] = krb_[i] + (slot) * SHM_KR; } } while (0)
; template <int MODE> ...
;     ...
;     for (int j = 1; j < NT; ++j) {
;         KADDR(ks); SBAR();
;         if constexpr (MODE != 0) { const bool ap = ACT(j - 1), ac = ACT(j); VFr fa; if (ap) vread<0>(fa, vb0 + vp * SHM_V); if (ac) qkt<MODE>(p0, p1, ka, kra, qr); if (ap) pv_pipe(o, vb0 + vp * SHM_V, fa, pa0, pa1, pa2, pa3); }
;         else { qkt<MODE>(p0, p1, ka, kra, qr); pv_d0(o, vb0 + vp * SHM_V, pa0, pa1, pa2, pa3); }
;         __syncthreads();
;         if (ACT(j)) { partialSM<MODE>(p0, p1, m_reg, mn, al, REL0(j), hi, NEEDM(j)); RESC(al); finishSM(p0, p1, al, l_reg, pa0, pa1, pa2, pa3); }
;         if (j + 2 < NT) { asm volatile("s_waitcnt vmcnt(0)" ::: "memory"); SWRITEX(sg, kw, vw); } if (j + 3 < NT) SLOAD((j + 3) * 64);
;         __syncthreads();
;         ks = (ks == 2) ? 0 : ks + 1; kw = (kw == 2) ? 0 : kw + 1; vp = (vp == 3) ? 0 : vp + 1; vw = (vw == 3) ? 0 : vw + 1;
;     }
.LBB0_294:
	s_add_i32 s4, s43, 1
	s_cmp_lg_u32 s43, 2
	s_cselect_b32 s43, s4, 0
	s_add_i32 s4, s45, 1
	s_cmp_lg_u32 s45, 2
	s_cselect_b32 s45, s4, 0
	s_add_i32 s4, s44, 1
	s_cmp_lg_u32 s44, 3
	s_cselect_b32 s44, s4, 0
	s_add_i32 s4, s42, 1
	s_cmp_lg_u32 s42, 3
	s_cselect_b32 s42, s4, 0
	s_add_i32 s0, s0, 1
	s_add_u32 s20, s20, 64
	v_add_f32_e32 v64, v64, v65
	s_addc_u32 s21, s21, 0
	s_mov_b64 s[4:5], 0x2000
	v_fmac_f32_e32 v64, v223, v224
	s_cmp_eq_u32 s40, s0
	v_lshl_add_u64 v[184:185], v[184:185], 0, s[4:5]
	s_cbranch_scc1 .Lm0_last_tile
	s_lshl_b32 s4, s43, 14
	s_lshl_b32 s5, s43, 13
	v_add_u32_e32 v248, s4, v213
	v_add_u32_e32 v249, s5, v214
	v_add_u32_e32 v250, s4, v215
	v_add_u32_e32 v251, s5, v216
	v_add_u32_e32 v252, s4, v217
	v_add_u32_e32 v253, s5, v218
	v_add_u32_e32 v188, s4, v219
	v_add_u32_e32 v191, s5, v220
	ds_read_b128 v[192:195], v248 offset:0x0
	ds_read_b128 v[196:199], v248 offset:0x2000
	ds_read_b128 v[224:227], v250 offset:0x0
	ds_read_b128 v[228:231], v250 offset:0x2000
	ds_read_b128 v[232:235], v252 offset:0x0
	ds_read_b128 v[236:239], v252 offset:0x2000
	ds_read_b128 v[240:243], v188 offset:0x0
	ds_read_b128 v[244:247], v188 offset:0x2000
	v_mov_b32_e32 v223, v64
	s_waitcnt lgkmcnt(8)
	s_barrier
	s_branch .LBB0_286
.Lm0_last_tile:
	s_waitcnt lgkmcnt(0)
	s_barrier
	v_mov_b32_e32 v192, 0xf149f2ca
	v_mov_b32_e32 v193, 0xc6ea6000
	v_mov_b32_e32 v194, 0x20000
	v_mov_b32_e32 v195, 0x40000
	v_mov_b32_e32 v196, 0x60000
	v_mov_b32_e32 v197, 0x80000
	v_mov_b32_e32 v198, 0xa0000
	v_mov_b32_e32 v199, 0xc0000
	v_mov_b32_e32 v200, 0xe0000
